# GEMM loader segments: m0 write moved ahead of the address add so the s_nop hazard filler is dropped (22 sites); diff loop head pinned (stacked on v17)
# baseline (speedup 1.0000x reference)
; #define PG8_STAGE(bufoff, gbase, voff) do { _Pragma("unroll") for (int _i = 0; _i < 2; ++_i) \
;         __builtin_amdgcn_global_load_lds((const unsigned*)((const char*)(gbase) + (voff)[_i]), (LAS unsigned*)(lds + (bufoff) + ldsw + _i * 8192), 16, 0, 0); } while (0)
; #define PG8_LDA(dst, b, h) do { _Pragma("unroll") for (int m = 0; m < 4; ++m) _Pragma("unroll") for (int k = 0; k < 2; ++k) dst[m][k] = *(const LAS bf16x8*)(lds + PG8_SA(b, h) + aoff + m * 2048 + k * 1024); } while (0)
; #define PG8_LDB(dst, b, h) do { _Pragma("unroll") for (int n = 0; n < 2; ++n) _Pragma("unroll") for (int k = 0; k < 2; ++k) dst[n][k] = *(const LAS bf16x8*)(lds + PG8_SB(b, h) + boff + n * 2048 + k * 1024); } while (0)
; #define PG8_WAIT_V(n) asm volatile("s_waitcnt vmcnt(" #n ")" ::: "memory")
; #define PG8_WAIT_L(n) asm volatile("s_waitcnt lgkmcnt(" #n ")" ::: "memory")
; #define PG8_BAR __builtin_amdgcn_s_barrier()
; #define PG8_SCHED __builtin_amdgcn_sched_barrier(0)
; template <class Epi>
; DI void gemm_phase(int wv, LAS unsigned char* lds, const GemmD g, const Epi& E) {
;     ...
;         const bool has_next = S.next(ui + 1, nxt);
;         const char* nA = has_next ? (const char*)g.A + (size_t)nxt.pm * 256 * g.lda * 2 : cA; const char* nB = has_next ? (const char*)g.Bt + PG8_BROW(nxt.pn) * (size_t)g.ldb * 2 : cB;
;         for (int t = 0; t < nt; t += 2) {
;             const bool last = (t == nt - 2);
;             const char* a1 = cA + (size_t)(t + 1) * kstep;
;             const char* a2 = last ? nA : cA + (size_t)(t + 2) * kstep; const char* b2 = last ? nB : cB + (size_t)(t + 2) * kstep;
;             const char* a3 = a2 + kstep; const char* b3 = b2 + kstep;
;             PG8_LDB(B0, 0, 0); PG8_SCHED; PG8_LDA(At, 0, 0); PG8_STAGE(PG8_SA(1, 1), a1 + hstepA, voffA);
;             PG8_WAIT_L(8); PG8_BAR; PG8_WAIT_L(0); PG8_MMA(0, 0, At, B0); PG8_BAR; PG8_SCHED;
;             PG8_LDB(B1, 0, 1); PG8_STAGE(PG8_SB(0, 0), b2, voffB);
;             PG8_BAR; PG8_WAIT_L(0); PG8_MMA(0, 1, At, B1); PG8_BAR;
;             PG8_LDA(At, 0, 1); PG8_STAGE(PG8_SA(0, 0), a2, voffA);
;             PG8_BAR; PG8_WAIT_L(0); PG8_MMA(1, 0, At, B0); PG8_BAR; PG8_SCHED;
;             PG8_STAGE(PG8_SB(0, 1), b2 + hstepB, voffB);
;             PG8_WAIT_V(6); PG8_BAR; PG8_MMA(1, 1, At, B1); PG8_BAR;
.LBB0_98:
	s_ashr_i32 s17, s16, 31
	s_lshl_b64 s[20:21], s[16:17], 19
	s_add_u32 s20, s6, s20
	s_addc_u32 s21, s7, s21
	s_and_b64 s[4:5], s[4:5], exec
	s_cselect_b32 s17, s21, s25
	s_cselect_b32 vcc_lo, s20, s24
	s_add_u32 s4, s24, 0x40080
	s_addc_u32 s5, s25, 0
	s_add_u32 vcc_hi, s22, 0x100
	s_addc_u32 s75, s23, 0
	s_mov_b32 s95, -2
	s_add_u32 s22, s4, 0xfffc0080
	s_addc_u32 s23, s5, -1
	s_add_i32 s3, 0, 0x10000
	v_add_u32_e32 v156, s3, v141
	ds_read_b128 v[144:147], v156
	ds_read_b128 v[148:151], v156 offset:1024
	ds_read_b128 v[152:155], v156 offset:2048
	ds_read_b128 v[156:159], v156 offset:3072
	s_cmp_eq_u32 s95, 12
	s_cselect_b32 s23, s17, s23
	s_cselect_b32 s22, vcc_lo, s22
	s_cselect_b32 s25, s19, s75
	s_cselect_b32 s24, s18, vcc_hi
	v_lshl_add_u64 v[164:165], s[4:5], 0, v[136:137]
	s_add_i32 m0, s15, 0xc000
	ds_read_b128 v[160:163], v143
	ds_read_b128 v[176:179], v143 offset:1024
	ds_read_b128 v[180:183], v143 offset:2048
	ds_read_b128 v[184:187], v143 offset:3072
	ds_read_b128 v[188:191], v143 offset:4096
	ds_read_b128 v[192:195], v143 offset:5120
	ds_read_b128 v[196:199], v143 offset:6144
	ds_read_b128 v[200:203], v143 offset:7168
	global_load_lds_dwordx4 v[164:165], off
	s_add_i32 m0, s15, 0xe000
	v_lshl_add_u64 v[164:165], s[4:5], 0, v[138:139]
	global_load_lds_dwordx4 v[164:165], off
	s_waitcnt lgkmcnt(8)
	s_barrier
	s_waitcnt lgkmcnt(0)
	s_waitcnt lgkmcnt(0)
	v_mfma_f32_16x16x32_bf16 v[126:129], v[144:147], v[160:163], 0
	v_mfma_f32_16x16x32_bf16 v[122:125], v[152:155], v[160:163], 0
	v_mfma_f32_16x16x32_bf16 v[118:121], v[144:147], v[180:183], 0
	v_mfma_f32_16x16x32_bf16 v[114:117], v[152:155], v[180:183], 0
	v_mfma_f32_16x16x32_bf16 v[102:105], v[144:147], v[188:191], 0
	v_mfma_f32_16x16x32_bf16 v[98:101], v[152:155], v[188:191], 0
	v_mfma_f32_16x16x32_bf16 v[86:89], v[144:147], v[196:199], 0
	v_mfma_f32_16x16x32_bf16 v[82:85], v[152:155], v[196:199], 0
	v_mfma_f32_16x16x32_bf16 v[126:129], v[148:151], v[176:179], v[126:129]
	v_mfma_f32_16x16x32_bf16 v[122:125], v[156:159], v[176:179], v[122:125]
	v_mfma_f32_16x16x32_bf16 v[118:121], v[148:151], v[184:187], v[118:121]
	v_mfma_f32_16x16x32_bf16 v[114:117], v[156:159], v[184:187], v[114:117]
	v_mfma_f32_16x16x32_bf16 v[102:105], v[148:151], v[192:195], v[102:105]
	v_mfma_f32_16x16x32_bf16 v[98:101], v[156:159], v[192:195], v[98:101]
	v_mfma_f32_16x16x32_bf16 v[86:89], v[148:151], v[200:203], v[86:89]
	v_mfma_f32_16x16x32_bf16 v[82:85], v[156:159], v[200:203], v[82:85]
	s_barrier
	s_add_i32 s2, 0, 0x14000
	v_add_u32_e32 v164, s2, v141
	s_add_i32 s3, s3, s37
	ds_read_b128 v[204:207], v164
	ds_read_b128 v[208:211], v164 offset:1024
	ds_read_b128 v[212:215], v164 offset:2048
	ds_read_b128 v[216:219], v164 offset:3072
	v_lshl_add_u64 v[164:165], s[24:25], 0, v[0:1]
	s_mov_b32 m0, s3
	v_lshl_add_u64 v[168:169], s[24:25], 0, v[130:131]
	global_load_lds_dwordx4 v[164:165], off
	s_add_i32 m0, s3, 0x2000
	s_nop 0
	global_load_lds_dwordx4 v[168:169], off
	s_barrier
	s_waitcnt lgkmcnt(0)
	s_waitcnt lgkmcnt(0)
	v_mfma_f32_16x16x32_bf16 v[110:113], v[204:207], v[160:163], 0
	v_mfma_f32_16x16x32_bf16 v[106:109], v[212:215], v[160:163], 0
	v_mfma_f32_16x16x32_bf16 v[94:97], v[204:207], v[180:183], 0
	v_mfma_f32_16x16x32_bf16 v[90:93], v[212:215], v[180:183], 0
	v_mfma_f32_16x16x32_bf16 v[78:81], v[204:207], v[188:191], 0
	v_mfma_f32_16x16x32_bf16 v[74:77], v[212:215], v[188:191], 0
	v_mfma_f32_16x16x32_bf16 v[70:73], v[204:207], v[196:199], 0
	v_mfma_f32_16x16x32_bf16 v[66:69], v[212:215], v[196:199], 0
	v_mfma_f32_16x16x32_bf16 v[110:113], v[208:211], v[176:179], v[110:113]
	v_mfma_f32_16x16x32_bf16 v[106:109], v[216:219], v[176:179], v[106:109]
	v_mfma_f32_16x16x32_bf16 v[94:97], v[208:211], v[184:187], v[94:97]
	v_mfma_f32_16x16x32_bf16 v[90:93], v[216:219], v[184:187], v[90:93]
	v_mfma_f32_16x16x32_bf16 v[78:81], v[208:211], v[192:195], v[78:81]
	v_mfma_f32_16x16x32_bf16 v[74:77], v[216:219], v[192:195], v[74:77]
	v_mfma_f32_16x16x32_bf16 v[70:73], v[208:211], v[200:203], v[70:73]
	v_mfma_f32_16x16x32_bf16 v[66:69], v[216:219], v[200:203], v[66:69]
	s_mov_b32 m0, s15
	v_lshl_add_u64 v[170:171], s[22:23], 0, v[134:135]
	s_barrier
	ds_read_b128 v[160:163], v143 offset:16384
	ds_read_b128 v[176:179], v143 offset:17408
	ds_read_b128 v[180:183], v143 offset:18432
	ds_read_b128 v[184:187], v143 offset:19456
	ds_read_b128 v[188:191], v143 offset:20480
	ds_read_b128 v[192:195], v143 offset:21504
	ds_read_b128 v[196:199], v143 offset:22528
	ds_read_b128 v[200:203], v143 offset:23552
	global_load_lds_dwordx4 v[170:171], off
	v_lshl_add_u64 v[220:221], s[22:23], 0, v[132:133]
	s_mov_b32 m0, s45
	s_nop 0
	global_load_lds_dwordx4 v[220:221], off
	s_barrier
	s_waitcnt lgkmcnt(0)
	s_waitcnt lgkmcnt(0)
	v_mfma_f32_16x16x32_bf16 v[62:65], v[144:147], v[160:163], 0
	v_mfma_f32_16x16x32_bf16 v[58:61], v[152:155], v[160:163], 0
	v_mfma_f32_16x16x32_bf16 v[54:57], v[144:147], v[180:183], 0
	v_mfma_f32_16x16x32_bf16 v[50:53], v[152:155], v[180:183], 0
	v_mfma_f32_16x16x32_bf16 v[38:41], v[144:147], v[188:191], 0
	v_mfma_f32_16x16x32_bf16 v[34:37], v[152:155], v[188:191], 0
	v_mfma_f32_16x16x32_bf16 v[22:25], v[144:147], v[196:199], 0
	v_mfma_f32_16x16x32_bf16 v[18:21], v[152:155], v[196:199], 0
	v_mfma_f32_16x16x32_bf16 v[62:65], v[148:151], v[176:179], v[62:65]
	v_mfma_f32_16x16x32_bf16 v[58:61], v[156:159], v[176:179], v[58:61]
	v_mfma_f32_16x16x32_bf16 v[54:57], v[148:151], v[184:187], v[54:57]
	v_mfma_f32_16x16x32_bf16 v[50:53], v[156:159], v[184:187], v[50:53]
	v_mfma_f32_16x16x32_bf16 v[38:41], v[148:151], v[192:195], v[38:41]
	v_mfma_f32_16x16x32_bf16 v[34:37], v[156:159], v[192:195], v[34:37]
	v_mfma_f32_16x16x32_bf16 v[22:25], v[148:151], v[200:203], v[22:25]
	v_mfma_f32_16x16x32_bf16 v[18:21], v[156:159], v[200:203], v[18:21]
	s_barrier
; #define PG8_STAGE(bufoff, gbase, voff) do { _Pragma("unroll") for (int _i = 0; _i < 2; ++_i) \
;         __builtin_amdgcn_global_load_lds((const unsigned*)((const char*)(gbase) + (voff)[_i]), (LAS unsigned*)(lds + (bufoff) + ldsw + _i * 8192), 16, 0, 0); } while (0)
; #define PG8_LDA(dst, b, h) do { _Pragma("unroll") for (int m = 0; m < 4; ++m) _Pragma("unroll") for (int k = 0; k < 2; ++k) dst[m][k] = *(const LAS bf16x8*)(lds + PG8_SA(b, h) + aoff + m * 2048 + k * 1024); } while (0)
; #define PG8_LDB(dst, b, h) do { _Pragma("unroll") for (int n = 0; n < 2; ++n) _Pragma("unroll") for (int k = 0; k < 2; ++k) dst[n][k] = *(const LAS bf16x8*)(lds + PG8_SB(b, h) + boff + n * 2048 + k * 1024); } while (0)
; #define PG8_MMA(ai, bj, At, Bt) do { __builtin_amdgcn_s_setprio(1); _Pragma("unroll") for (int m = 0; m < 4; ++m) _Pragma("unroll") for (int n = 0; n < 2; ++n) _Pragma("unroll") for (int k = 0; k < 2; ++k) \
;         acc[ai][bj][m][n] = __builtin_amdgcn_mfma_f32_16x16x32_bf16(Bt[n][k], At[m][k], acc[ai][bj][m][n], 0, 0, 0); __builtin_amdgcn_s_setprio(0); } while (0)
; #define PG8_WAIT_V(n) asm volatile("s_waitcnt vmcnt(" #n ")" ::: "memory")
; #define PG8_WAIT_L(n) asm volatile("s_waitcnt lgkmcnt(" #n ")" ::: "memory")
; #define PG8_BAR __builtin_amdgcn_s_barrier()
; #define PG8_SCHED __builtin_amdgcn_sched_barrier(0)
; template <class Epi>
; DI void gemm_phase(int wv, LAS unsigned char* lds, const GemmD g, const Epi& E) {
;     ...
;             PG8_STAGE(PG8_SB(0, 1), b2 + hstepB, voffB);
;             PG8_WAIT_V(6); PG8_BAR; PG8_MMA(1, 1, At, B1); PG8_BAR;
;             PG8_LDB(B0, 1, 0); PG8_SCHED; PG8_LDA(At, 1, 0); PG8_STAGE(PG8_SA(0, 1), a2 + hstepA, voffA);
;             PG8_WAIT_L(8); PG8_BAR; PG8_WAIT_L(0); PG8_MMA(0, 0, At, B0); PG8_BAR; PG8_SCHED;
;             PG8_LDB(B1, 1, 1); PG8_STAGE(PG8_SB(1, 0), b3, voffB);
;             PG8_BAR; PG8_WAIT_L(0); PG8_MMA(0, 1, At, B1); PG8_BAR;
;             PG8_LDA(At, 1, 1); PG8_STAGE(PG8_SA(1, 0), a3, voffA);
;             PG8_BAR; PG8_WAIT_L(0); PG8_MMA(1, 0, At, B0); PG8_BAR; PG8_SCHED;
	s_add_u32 s24, s24, s36
	s_addc_u32 s25, s25, 0
	s_add_i32 s2, s2, s37
	v_lshl_add_u64 v[222:223], s[24:25], 0, v[0:1]
	s_mov_b32 m0, s2
	v_lshl_add_u64 v[224:225], s[24:25], 0, v[130:131]
	global_load_lds_dwordx4 v[222:223], off
	s_add_i32 m0, s2, 0x2000
	s_nop 0
	global_load_lds_dwordx4 v[224:225], off
	s_waitcnt vmcnt(6)
	s_barrier
	v_mfma_f32_16x16x32_bf16 v[46:49], v[204:207], v[160:163], 0
	v_mfma_f32_16x16x32_bf16 v[42:45], v[212:215], v[160:163], 0
	v_mfma_f32_16x16x32_bf16 v[30:33], v[204:207], v[180:183], 0
	v_mfma_f32_16x16x32_bf16 v[26:29], v[212:215], v[180:183], 0
	v_mfma_f32_16x16x32_bf16 v[14:17], v[204:207], v[188:191], 0
	v_mfma_f32_16x16x32_bf16 v[10:13], v[212:215], v[188:191], 0
	v_mfma_f32_16x16x32_bf16 v[6:9], v[204:207], v[196:199], 0
	v_mfma_f32_16x16x32_bf16 v[2:5], v[212:215], v[196:199], 0
	v_mfma_f32_16x16x32_bf16 v[46:49], v[208:211], v[176:179], v[46:49]
	v_mfma_f32_16x16x32_bf16 v[42:45], v[216:219], v[176:179], v[42:45]
	v_mfma_f32_16x16x32_bf16 v[30:33], v[208:211], v[184:187], v[30:33]
	v_mfma_f32_16x16x32_bf16 v[26:29], v[216:219], v[184:187], v[26:29]
	v_mfma_f32_16x16x32_bf16 v[14:17], v[208:211], v[192:195], v[14:17]
	v_mfma_f32_16x16x32_bf16 v[10:13], v[216:219], v[192:195], v[10:13]
	v_mfma_f32_16x16x32_bf16 v[6:9], v[208:211], v[200:203], v[6:9]
	v_mfma_f32_16x16x32_bf16 v[2:5], v[216:219], v[200:203], v[2:5]
	s_add_i32 s2, 0, 0x18000
	v_add_u32_e32 v156, s2, v141
	s_barrier
	ds_read_b128 v[144:147], v156
	ds_read_b128 v[148:151], v156 offset:1024
	ds_read_b128 v[152:155], v156 offset:2048
	ds_read_b128 v[156:159], v156 offset:3072
	s_add_u32 s22, s22, 0x40000
	s_addc_u32 s23, s23, 0
	s_mov_b32 m0, s82
	v_lshl_add_u64 v[204:205], s[22:23], 0, v[134:135]
	ds_read_b128 v[160:163], v143 offset:32768
	ds_read_b128 v[176:179], v143 offset:33792
	ds_read_b128 v[180:183], v143 offset:34816
	ds_read_b128 v[184:187], v143 offset:35840
	ds_read_b128 v[188:191], v143 offset:36864
	ds_read_b128 v[192:195], v143 offset:37888
	ds_read_b128 v[196:199], v143 offset:38912
	ds_read_b128 v[200:203], v143 offset:39936
	global_load_lds_dwordx4 v[204:205], off
	v_lshl_add_u64 v[204:205], s[22:23], 0, v[132:133]
	s_mov_b32 m0, s83
	s_nop 0
	global_load_lds_dwordx4 v[204:205], off
	s_waitcnt lgkmcnt(8)
	s_barrier
	s_waitcnt lgkmcnt(0)
	s_waitcnt lgkmcnt(0)
	v_mfma_f32_16x16x32_bf16 v[126:129], v[144:147], v[160:163], v[126:129]
	v_mfma_f32_16x16x32_bf16 v[122:125], v[152:155], v[160:163], v[122:125]
	v_mfma_f32_16x16x32_bf16 v[118:121], v[144:147], v[180:183], v[118:121]
	v_mfma_f32_16x16x32_bf16 v[114:117], v[152:155], v[180:183], v[114:117]
	v_mfma_f32_16x16x32_bf16 v[102:105], v[144:147], v[188:191], v[102:105]
	v_mfma_f32_16x16x32_bf16 v[98:101], v[152:155], v[188:191], v[98:101]
	v_mfma_f32_16x16x32_bf16 v[86:89], v[144:147], v[196:199], v[86:89]
	v_mfma_f32_16x16x32_bf16 v[82:85], v[152:155], v[196:199], v[82:85]
	v_mfma_f32_16x16x32_bf16 v[126:129], v[148:151], v[176:179], v[126:129]
	v_mfma_f32_16x16x32_bf16 v[122:125], v[156:159], v[176:179], v[122:125]
	v_mfma_f32_16x16x32_bf16 v[118:121], v[148:151], v[184:187], v[118:121]
	v_mfma_f32_16x16x32_bf16 v[114:117], v[156:159], v[184:187], v[114:117]
	v_mfma_f32_16x16x32_bf16 v[102:105], v[148:151], v[192:195], v[102:105]
	v_mfma_f32_16x16x32_bf16 v[98:101], v[156:159], v[192:195], v[98:101]
	v_mfma_f32_16x16x32_bf16 v[86:89], v[148:151], v[200:203], v[86:89]
	v_mfma_f32_16x16x32_bf16 v[82:85], v[156:159], v[200:203], v[82:85]
	s_barrier
	s_add_i32 s3, 0, 0x1c000
	s_add_i32 s2, s2, s37
	v_add_u32_e32 v216, s3, v141
	v_lshl_add_u64 v[164:165], v[164:165], 0, s[58:59]
	s_mov_b32 m0, s2
	ds_read_b128 v[204:207], v216
	ds_read_b128 v[208:211], v216 offset:1024
	ds_read_b128 v[212:215], v216 offset:2048
	ds_read_b128 v[216:219], v216 offset:3072
	global_load_lds_dwordx4 v[164:165], off
	s_add_i32 m0, s2, 0x2000
	v_lshl_add_u64 v[164:165], v[168:169], 0, s[58:59]
	global_load_lds_dwordx4 v[164:165], off
	s_barrier
	s_waitcnt lgkmcnt(0)
	s_waitcnt lgkmcnt(0)
	v_mfma_f32_16x16x32_bf16 v[110:113], v[204:207], v[160:163], v[110:113]
	v_mfma_f32_16x16x32_bf16 v[106:109], v[212:215], v[160:163], v[106:109]
	v_mfma_f32_16x16x32_bf16 v[94:97], v[204:207], v[180:183], v[94:97]
	v_mfma_f32_16x16x32_bf16 v[90:93], v[212:215], v[180:183], v[90:93]
	v_mfma_f32_16x16x32_bf16 v[78:81], v[204:207], v[188:191], v[78:81]
	v_mfma_f32_16x16x32_bf16 v[74:77], v[212:215], v[188:191], v[74:77]
	v_mfma_f32_16x16x32_bf16 v[70:73], v[204:207], v[196:199], v[70:73]
	v_mfma_f32_16x16x32_bf16 v[66:69], v[212:215], v[196:199], v[66:69]
	v_mfma_f32_16x16x32_bf16 v[110:113], v[208:211], v[176:179], v[110:113]
	v_mfma_f32_16x16x32_bf16 v[106:109], v[216:219], v[176:179], v[106:109]
	v_mfma_f32_16x16x32_bf16 v[94:97], v[208:211], v[184:187], v[94:97]
	v_mfma_f32_16x16x32_bf16 v[90:93], v[216:219], v[184:187], v[90:93]
	v_mfma_f32_16x16x32_bf16 v[78:81], v[208:211], v[192:195], v[78:81]
	v_mfma_f32_16x16x32_bf16 v[74:77], v[216:219], v[192:195], v[74:77]
	v_mfma_f32_16x16x32_bf16 v[70:73], v[208:211], v[200:203], v[70:73]
	v_mfma_f32_16x16x32_bf16 v[66:69], v[216:219], v[200:203], v[66:69]
	s_mov_b32 m0, s84
	v_lshl_add_u64 v[164:165], v[170:171], 0, s[58:59]
	s_barrier
	ds_read_b128 v[160:163], v143 offset:49152
	ds_read_b128 v[176:179], v143 offset:50176
	ds_read_b128 v[180:183], v143 offset:51200
	ds_read_b128 v[184:187], v143 offset:52224
	ds_read_b128 v[188:191], v143 offset:53248
	ds_read_b128 v[192:195], v143 offset:54272
	ds_read_b128 v[196:199], v143 offset:55296
	ds_read_b128 v[200:203], v143 offset:56320
	global_load_lds_dwordx4 v[164:165], off
	v_lshl_add_u64 v[164:165], v[220:221], 0, s[58:59]
	s_mov_b32 m0, s85
	s_nop 0
	global_load_lds_dwordx4 v[164:165], off
	s_barrier
; #define PG8_STAGE(bufoff, gbase, voff) do { _Pragma("unroll") for (int _i = 0; _i < 2; ++_i) \
;         __builtin_amdgcn_global_load_lds((const unsigned*)((const char*)(gbase) + (voff)[_i]), (LAS unsigned*)(lds + (bufoff) + ldsw + _i * 8192), 16, 0, 0); } while (0)
; #define PG8_LDA(dst, b, h) do { _Pragma("unroll") for (int m = 0; m < 4; ++m) _Pragma("unroll") for (int k = 0; k < 2; ++k) dst[m][k] = *(const LAS bf16x8*)(lds + PG8_SA(b, h) + aoff + m * 2048 + k * 1024); } while (0)
; #define PG8_LDB(dst, b, h) do { _Pragma("unroll") for (int n = 0; n < 2; ++n) _Pragma("unroll") for (int k = 0; k < 2; ++k) dst[n][k] = *(const LAS bf16x8*)(lds + PG8_SB(b, h) + boff + n * 2048 + k * 1024); } while (0)
; #define PG8_MMA(ai, bj, At, Bt) do { __builtin_amdgcn_s_setprio(1); _Pragma("unroll") for (int m = 0; m < 4; ++m) _Pragma("unroll") for (int n = 0; n < 2; ++n) _Pragma("unroll") for (int k = 0; k < 2; ++k) \
;         acc[ai][bj][m][n] = __builtin_amdgcn_mfma_f32_16x16x32_bf16(Bt[n][k], At[m][k], acc[ai][bj][m][n], 0, 0, 0); __builtin_amdgcn_s_setprio(0); } while (0)
; #define PG8_WAIT_V(n) asm volatile("s_waitcnt vmcnt(" #n ")" ::: "memory")
; #define PG8_WAIT_L(n) asm volatile("s_waitcnt lgkmcnt(" #n ")" ::: "memory")
; template <class Epi>
; DI void gemm_phase(int wv, LAS unsigned char* lds, const GemmD g, const Epi& E) {
;     ...
;             const bool last = (t == nt - 2);
;             const char* a1 = cA + (size_t)(t + 1) * kstep;
;             const char* a2 = last ? nA : cA + (size_t)(t + 2) * kstep; const char* b2 = last ? nB : cB + (size_t)(t + 2) * kstep;
;             const char* a3 = a2 + kstep; const char* b3 = b2 + kstep;
;             PG8_LDB(B0, 0, 0); PG8_SCHED; PG8_LDA(At, 0, 0); PG8_STAGE(PG8_SA(1, 1), a1 + hstepA, voffA);
;             PG8_WAIT_L(8); PG8_BAR; PG8_WAIT_L(0); PG8_MMA(0, 0, At, B0); PG8_BAR; PG8_SCHED;
;     ...
;             PG8_WAIT_L(8); PG8_BAR; PG8_WAIT_L(0); PG8_MMA(0, 0, At, B0); PG8_BAR; PG8_SCHED;
;             PG8_LDB(B1, 1, 1); PG8_STAGE(PG8_SB(1, 0), b3, voffB);
;             PG8_BAR; PG8_WAIT_L(0); PG8_MMA(0, 1, At, B1); PG8_BAR;
;             PG8_LDA(At, 1, 1); PG8_STAGE(PG8_SA(1, 0), a3, voffA);
;             PG8_BAR; PG8_WAIT_L(0); PG8_MMA(1, 0, At, B0); PG8_BAR; PG8_SCHED;
;             PG8_STAGE(PG8_SB(1, 1), b3 + hstepB, voffB);
;             PG8_WAIT_V(6); PG8_BAR; PG8_MMA(1, 1, At, B1); PG8_BAR;
	s_waitcnt lgkmcnt(0)
	s_waitcnt lgkmcnt(0)
	v_mfma_f32_16x16x32_bf16 v[62:65], v[144:147], v[160:163], v[62:65]
	v_mfma_f32_16x16x32_bf16 v[58:61], v[152:155], v[160:163], v[58:61]
	v_mfma_f32_16x16x32_bf16 v[54:57], v[144:147], v[180:183], v[54:57]
	v_mfma_f32_16x16x32_bf16 v[50:53], v[152:155], v[180:183], v[50:53]
	v_mfma_f32_16x16x32_bf16 v[38:41], v[144:147], v[188:191], v[38:41]
	v_mfma_f32_16x16x32_bf16 v[34:37], v[152:155], v[188:191], v[34:37]
	v_mfma_f32_16x16x32_bf16 v[22:25], v[144:147], v[196:199], v[22:25]
	v_mfma_f32_16x16x32_bf16 v[18:21], v[152:155], v[196:199], v[18:21]
	v_mfma_f32_16x16x32_bf16 v[62:65], v[148:151], v[176:179], v[62:65]
	v_mfma_f32_16x16x32_bf16 v[58:61], v[156:159], v[176:179], v[58:61]
	v_mfma_f32_16x16x32_bf16 v[54:57], v[148:151], v[184:187], v[54:57]
	v_mfma_f32_16x16x32_bf16 v[50:53], v[156:159], v[184:187], v[50:53]
	v_mfma_f32_16x16x32_bf16 v[38:41], v[148:151], v[192:195], v[38:41]
	v_mfma_f32_16x16x32_bf16 v[34:37], v[156:159], v[192:195], v[34:37]
	v_mfma_f32_16x16x32_bf16 v[22:25], v[148:151], v[200:203], v[22:25]
	v_mfma_f32_16x16x32_bf16 v[18:21], v[156:159], v[200:203], v[18:21]
	s_barrier
	s_add_i32 s2, s3, s37
	v_lshl_add_u64 v[144:145], v[222:223], 0, s[58:59]
	s_mov_b32 m0, s2
	s_nop 0
	global_load_lds_dwordx4 v[144:145], off
	s_add_i32 m0, s2, 0x2000
	v_lshl_add_u64 v[144:145], v[224:225], 0, s[58:59]
	global_load_lds_dwordx4 v[144:145], off
	s_waitcnt vmcnt(6)
	s_barrier
	v_mfma_f32_16x16x32_bf16 v[46:49], v[204:207], v[160:163], v[46:49]
	v_mfma_f32_16x16x32_bf16 v[42:45], v[212:215], v[160:163], v[42:45]
	v_mfma_f32_16x16x32_bf16 v[30:33], v[204:207], v[180:183], v[30:33]
	v_mfma_f32_16x16x32_bf16 v[26:29], v[212:215], v[180:183], v[26:29]
	v_mfma_f32_16x16x32_bf16 v[14:17], v[204:207], v[188:191], v[14:17]
	v_mfma_f32_16x16x32_bf16 v[10:13], v[212:215], v[188:191], v[10:13]
	v_mfma_f32_16x16x32_bf16 v[6:9], v[204:207], v[196:199], v[6:9]
	v_mfma_f32_16x16x32_bf16 v[2:5], v[212:215], v[196:199], v[2:5]
	v_mfma_f32_16x16x32_bf16 v[46:49], v[208:211], v[176:179], v[46:49]
	v_mfma_f32_16x16x32_bf16 v[42:45], v[216:219], v[176:179], v[42:45]
	v_mfma_f32_16x16x32_bf16 v[30:33], v[208:211], v[184:187], v[30:33]
	v_mfma_f32_16x16x32_bf16 v[26:29], v[216:219], v[184:187], v[26:29]
	v_mfma_f32_16x16x32_bf16 v[14:17], v[208:211], v[192:195], v[14:17]
	v_mfma_f32_16x16x32_bf16 v[10:13], v[216:219], v[192:195], v[10:13]
	v_mfma_f32_16x16x32_bf16 v[6:9], v[208:211], v[200:203], v[6:9]
	v_mfma_f32_16x16x32_bf16 v[2:5], v[216:219], v[200:203], v[2:5]
	s_add_i32 s95, s95, 2
	s_add_u32 s4, s4, 0x100
	s_addc_u32 s5, s5, 0
	s_add_u32 vcc_hi, vcc_hi, 0x100
	s_addc_u32 s75, s75, 0
	s_cmp_gt_u32 s95, 13
	s_barrier
	s_cbranch_scc0 .LBB0_99
	s_branch .Lgemm_epi_a
	.p2align 6
.LBB0_99:
	s_add_u32 s22, s4, 0xfffc0080
	s_addc_u32 s23, s5, -1
	s_add_i32 s3, 0, 0x10000
	v_add_u32_e32 v156, s3, v141
	ds_read_b128 v[144:147], v156
	ds_read_b128 v[148:151], v156 offset:1024
	ds_read_b128 v[152:155], v156 offset:2048
	ds_read_b128 v[156:159], v156 offset:3072
	s_cmp_eq_u32 s95, 12
	s_cselect_b32 s23, s17, s23
	s_cselect_b32 s22, vcc_lo, s22
	s_cselect_b32 s25, s19, s75
	s_cselect_b32 s24, s18, vcc_hi
	v_lshl_add_u64 v[164:165], s[4:5], 0, v[136:137]
	s_add_i32 m0, s15, 0xc000
	ds_read_b128 v[160:163], v143
	ds_read_b128 v[176:179], v143 offset:1024
	ds_read_b128 v[180:183], v143 offset:2048
	ds_read_b128 v[184:187], v143 offset:3072
	ds_read_b128 v[188:191], v143 offset:4096
	ds_read_b128 v[192:195], v143 offset:5120
	ds_read_b128 v[196:199], v143 offset:6144
	ds_read_b128 v[200:203], v143 offset:7168
	global_load_lds_dwordx4 v[164:165], off
	s_add_i32 m0, s15, 0xe000
	v_lshl_add_u64 v[164:165], s[4:5], 0, v[138:139]
	global_load_lds_dwordx4 v[164:165], off
	s_waitcnt lgkmcnt(8)
	s_barrier
	s_waitcnt lgkmcnt(0)
	s_waitcnt lgkmcnt(0)
	v_mfma_f32_16x16x32_bf16 v[126:129], v[144:147], v[160:163], v[126:129]
	v_mfma_f32_16x16x32_bf16 v[122:125], v[152:155], v[160:163], v[122:125]
	v_mfma_f32_16x16x32_bf16 v[118:121], v[144:147], v[180:183], v[118:121]
	v_mfma_f32_16x16x32_bf16 v[114:117], v[152:155], v[180:183], v[114:117]
	v_mfma_f32_16x16x32_bf16 v[102:105], v[144:147], v[188:191], v[102:105]
	v_mfma_f32_16x16x32_bf16 v[98:101], v[152:155], v[188:191], v[98:101]
	v_mfma_f32_16x16x32_bf16 v[86:89], v[144:147], v[196:199], v[86:89]
	v_mfma_f32_16x16x32_bf16 v[82:85], v[152:155], v[196:199], v[82:85]
	v_mfma_f32_16x16x32_bf16 v[126:129], v[148:151], v[176:179], v[126:129]
	v_mfma_f32_16x16x32_bf16 v[122:125], v[156:159], v[176:179], v[122:125]
	v_mfma_f32_16x16x32_bf16 v[118:121], v[148:151], v[184:187], v[118:121]
	v_mfma_f32_16x16x32_bf16 v[114:117], v[156:159], v[184:187], v[114:117]
	v_mfma_f32_16x16x32_bf16 v[102:105], v[148:151], v[192:195], v[102:105]
	v_mfma_f32_16x16x32_bf16 v[98:101], v[156:159], v[192:195], v[98:101]
	v_mfma_f32_16x16x32_bf16 v[86:89], v[148:151], v[200:203], v[86:89]
	v_mfma_f32_16x16x32_bf16 v[82:85], v[156:159], v[200:203], v[82:85]
	s_barrier
	s_add_i32 s2, 0, 0x14000
	v_add_u32_e32 v164, s2, v141
	s_add_i32 s3, s3, s37
	ds_read_b128 v[204:207], v164
	ds_read_b128 v[208:211], v164 offset:1024
	ds_read_b128 v[212:215], v164 offset:2048
	ds_read_b128 v[216:219], v164 offset:3072
	v_lshl_add_u64 v[164:165], s[24:25], 0, v[0:1]
	s_mov_b32 m0, s3
	v_lshl_add_u64 v[168:169], s[24:25], 0, v[130:131]
	global_load_lds_dwordx4 v[164:165], off
	s_add_i32 m0, s3, 0x2000
	s_nop 0
	global_load_lds_dwordx4 v[168:169], off
	s_barrier
; #define PG8_STAGE(bufoff, gbase, voff) do { _Pragma("unroll") for (int _i = 0; _i < 2; ++_i) \
;         __builtin_amdgcn_global_load_lds((const unsigned*)((const char*)(gbase) + (voff)[_i]), (LAS unsigned*)(lds + (bufoff) + ldsw + _i * 8192), 16, 0, 0); } while (0)
; #define PG8_LDA(dst, b, h) do { _Pragma("unroll") for (int m = 0; m < 4; ++m) _Pragma("unroll") for (int k = 0; k < 2; ++k) dst[m][k] = *(const LAS bf16x8*)(lds + PG8_SA(b, h) + aoff + m * 2048 + k * 1024); } while (0)
; #define PG8_LDB(dst, b, h) do { _Pragma("unroll") for (int n = 0; n < 2; ++n) _Pragma("unroll") for (int k = 0; k < 2; ++k) dst[n][k] = *(const LAS bf16x8*)(lds + PG8_SB(b, h) + boff + n * 2048 + k * 1024); } while (0)
; #define PG8_MMA(ai, bj, At, Bt) do { __builtin_amdgcn_s_setprio(1); _Pragma("unroll") for (int m = 0; m < 4; ++m) _Pragma("unroll") for (int n = 0; n < 2; ++n) _Pragma("unroll") for (int k = 0; k < 2; ++k) \
;         acc[ai][bj][m][n] = __builtin_amdgcn_mfma_f32_16x16x32_bf16(Bt[n][k], At[m][k], acc[ai][bj][m][n], 0, 0, 0); __builtin_amdgcn_s_setprio(0); } while (0)
; #define PG8_WAIT_V(n) asm volatile("s_waitcnt vmcnt(" #n ")" ::: "memory")
; #define PG8_WAIT_L(n) asm volatile("s_waitcnt lgkmcnt(" #n ")" ::: "memory")
; #define PG8_BAR __builtin_amdgcn_s_barrier()
; #define PG8_SCHED __builtin_amdgcn_sched_barrier(0)
; template <class Epi>
; DI void gemm_phase(int wv, LAS unsigned char* lds, const GemmD g, const Epi& E) {
;     ...
;             PG8_WAIT_L(8); PG8_BAR; PG8_WAIT_L(0); PG8_MMA(0, 0, At, B0); PG8_BAR; PG8_SCHED;
;             PG8_LDB(B1, 0, 1); PG8_STAGE(PG8_SB(0, 0), b2, voffB);
;             PG8_BAR; PG8_WAIT_L(0); PG8_MMA(0, 1, At, B1); PG8_BAR;
;             PG8_LDA(At, 0, 1); PG8_STAGE(PG8_SA(0, 0), a2, voffA);
;             PG8_BAR; PG8_WAIT_L(0); PG8_MMA(1, 0, At, B0); PG8_BAR; PG8_SCHED;
;             PG8_STAGE(PG8_SB(0, 1), b2 + hstepB, voffB);
;             PG8_WAIT_V(6); PG8_BAR; PG8_MMA(1, 1, At, B1); PG8_BAR;
;             PG8_LDB(B0, 1, 0); PG8_SCHED; PG8_LDA(At, 1, 0); PG8_STAGE(PG8_SA(0, 1), a2 + hstepA, voffA);
;             PG8_WAIT_L(8); PG8_BAR; PG8_WAIT_L(0); PG8_MMA(0, 0, At, B0); PG8_BAR; PG8_SCHED;
;             PG8_LDB(B1, 1, 1); PG8_STAGE(PG8_SB(1, 0), b3, voffB);
;             PG8_BAR; PG8_WAIT_L(0); PG8_MMA(0, 1, At, B1); PG8_BAR;
	s_waitcnt lgkmcnt(0)
	s_waitcnt lgkmcnt(0)
	v_mfma_f32_16x16x32_bf16 v[110:113], v[204:207], v[160:163], v[110:113]
	v_mfma_f32_16x16x32_bf16 v[106:109], v[212:215], v[160:163], v[106:109]
	v_mfma_f32_16x16x32_bf16 v[94:97], v[204:207], v[180:183], v[94:97]
	v_mfma_f32_16x16x32_bf16 v[90:93], v[212:215], v[180:183], v[90:93]
	v_mfma_f32_16x16x32_bf16 v[78:81], v[204:207], v[188:191], v[78:81]
	v_mfma_f32_16x16x32_bf16 v[74:77], v[212:215], v[188:191], v[74:77]
	v_mfma_f32_16x16x32_bf16 v[70:73], v[204:207], v[196:199], v[70:73]
	v_mfma_f32_16x16x32_bf16 v[66:69], v[212:215], v[196:199], v[66:69]
	v_mfma_f32_16x16x32_bf16 v[110:113], v[208:211], v[176:179], v[110:113]
	v_mfma_f32_16x16x32_bf16 v[106:109], v[216:219], v[176:179], v[106:109]
	v_mfma_f32_16x16x32_bf16 v[94:97], v[208:211], v[184:187], v[94:97]
	v_mfma_f32_16x16x32_bf16 v[90:93], v[216:219], v[184:187], v[90:93]
	v_mfma_f32_16x16x32_bf16 v[78:81], v[208:211], v[192:195], v[78:81]
	v_mfma_f32_16x16x32_bf16 v[74:77], v[216:219], v[192:195], v[74:77]
	v_mfma_f32_16x16x32_bf16 v[70:73], v[208:211], v[200:203], v[70:73]
	v_mfma_f32_16x16x32_bf16 v[66:69], v[216:219], v[200:203], v[66:69]
	s_mov_b32 m0, s15
	v_lshl_add_u64 v[170:171], s[22:23], 0, v[134:135]
	s_barrier
	ds_read_b128 v[160:163], v143 offset:16384
	ds_read_b128 v[176:179], v143 offset:17408
	ds_read_b128 v[180:183], v143 offset:18432
	ds_read_b128 v[184:187], v143 offset:19456
	ds_read_b128 v[188:191], v143 offset:20480
	ds_read_b128 v[192:195], v143 offset:21504
	ds_read_b128 v[196:199], v143 offset:22528
	ds_read_b128 v[200:203], v143 offset:23552
	global_load_lds_dwordx4 v[170:171], off
	v_lshl_add_u64 v[220:221], s[22:23], 0, v[132:133]
	s_mov_b32 m0, s45
	s_nop 0
	global_load_lds_dwordx4 v[220:221], off
	s_barrier
	s_waitcnt lgkmcnt(0)
	s_waitcnt lgkmcnt(0)
	v_mfma_f32_16x16x32_bf16 v[62:65], v[144:147], v[160:163], v[62:65]
	v_mfma_f32_16x16x32_bf16 v[58:61], v[152:155], v[160:163], v[58:61]
	v_mfma_f32_16x16x32_bf16 v[54:57], v[144:147], v[180:183], v[54:57]
	v_mfma_f32_16x16x32_bf16 v[50:53], v[152:155], v[180:183], v[50:53]
	v_mfma_f32_16x16x32_bf16 v[38:41], v[144:147], v[188:191], v[38:41]
	v_mfma_f32_16x16x32_bf16 v[34:37], v[152:155], v[188:191], v[34:37]
	v_mfma_f32_16x16x32_bf16 v[22:25], v[144:147], v[196:199], v[22:25]
	v_mfma_f32_16x16x32_bf16 v[18:21], v[152:155], v[196:199], v[18:21]
	v_mfma_f32_16x16x32_bf16 v[62:65], v[148:151], v[176:179], v[62:65]
	v_mfma_f32_16x16x32_bf16 v[58:61], v[156:159], v[176:179], v[58:61]
	v_mfma_f32_16x16x32_bf16 v[54:57], v[148:151], v[184:187], v[54:57]
	v_mfma_f32_16x16x32_bf16 v[50:53], v[156:159], v[184:187], v[50:53]
	v_mfma_f32_16x16x32_bf16 v[38:41], v[148:151], v[192:195], v[38:41]
	v_mfma_f32_16x16x32_bf16 v[34:37], v[156:159], v[192:195], v[34:37]
	v_mfma_f32_16x16x32_bf16 v[22:25], v[148:151], v[200:203], v[22:25]
	v_mfma_f32_16x16x32_bf16 v[18:21], v[156:159], v[200:203], v[18:21]
	s_barrier
	s_add_u32 s24, s24, s36
	s_addc_u32 s25, s25, 0
	s_add_i32 s2, s2, s37
	v_lshl_add_u64 v[222:223], s[24:25], 0, v[0:1]
	s_mov_b32 m0, s2
	v_lshl_add_u64 v[224:225], s[24:25], 0, v[130:131]
	global_load_lds_dwordx4 v[222:223], off
	s_add_i32 m0, s2, 0x2000
	s_nop 0
	global_load_lds_dwordx4 v[224:225], off
	s_waitcnt vmcnt(6)
	s_barrier
	v_mfma_f32_16x16x32_bf16 v[46:49], v[204:207], v[160:163], v[46:49]
	v_mfma_f32_16x16x32_bf16 v[42:45], v[212:215], v[160:163], v[42:45]
	v_mfma_f32_16x16x32_bf16 v[30:33], v[204:207], v[180:183], v[30:33]
	v_mfma_f32_16x16x32_bf16 v[26:29], v[212:215], v[180:183], v[26:29]
	v_mfma_f32_16x16x32_bf16 v[14:17], v[204:207], v[188:191], v[14:17]
	v_mfma_f32_16x16x32_bf16 v[10:13], v[212:215], v[188:191], v[10:13]
	v_mfma_f32_16x16x32_bf16 v[6:9], v[204:207], v[196:199], v[6:9]
	v_mfma_f32_16x16x32_bf16 v[2:5], v[212:215], v[196:199], v[2:5]
	v_mfma_f32_16x16x32_bf16 v[46:49], v[208:211], v[176:179], v[46:49]
	v_mfma_f32_16x16x32_bf16 v[42:45], v[216:219], v[176:179], v[42:45]
	v_mfma_f32_16x16x32_bf16 v[30:33], v[208:211], v[184:187], v[30:33]
	v_mfma_f32_16x16x32_bf16 v[26:29], v[216:219], v[184:187], v[26:29]
	v_mfma_f32_16x16x32_bf16 v[14:17], v[208:211], v[192:195], v[14:17]
	v_mfma_f32_16x16x32_bf16 v[10:13], v[216:219], v[192:195], v[10:13]
	v_mfma_f32_16x16x32_bf16 v[6:9], v[208:211], v[200:203], v[6:9]
	v_mfma_f32_16x16x32_bf16 v[2:5], v[216:219], v[200:203], v[2:5]
	s_add_i32 s2, 0, 0x18000
	v_add_u32_e32 v156, s2, v141
	s_barrier
	ds_read_b128 v[144:147], v156
	ds_read_b128 v[148:151], v156 offset:1024
	ds_read_b128 v[152:155], v156 offset:2048
	ds_read_b128 v[156:159], v156 offset:3072
	s_add_u32 s22, s22, 0x40000
	s_addc_u32 s23, s23, 0
	s_mov_b32 m0, s82
	v_lshl_add_u64 v[204:205], s[22:23], 0, v[134:135]
	ds_read_b128 v[160:163], v143 offset:32768
	ds_read_b128 v[176:179], v143 offset:33792
	ds_read_b128 v[180:183], v143 offset:34816
	ds_read_b128 v[184:187], v143 offset:35840
	ds_read_b128 v[188:191], v143 offset:36864
	ds_read_b128 v[192:195], v143 offset:37888
	ds_read_b128 v[196:199], v143 offset:38912
	ds_read_b128 v[200:203], v143 offset:39936
	global_load_lds_dwordx4 v[204:205], off
	v_lshl_add_u64 v[204:205], s[22:23], 0, v[132:133]
	s_mov_b32 m0, s83
	s_nop 0
	global_load_lds_dwordx4 v[204:205], off
	s_waitcnt lgkmcnt(8)
	s_barrier
; #define PG8_STAGE(bufoff, gbase, voff) do { _Pragma("unroll") for (int _i = 0; _i < 2; ++_i) \
;         __builtin_amdgcn_global_load_lds((const unsigned*)((const char*)(gbase) + (voff)[_i]), (LAS unsigned*)(lds + (bufoff) + ldsw + _i * 8192), 16, 0, 0); } while (0)
; #define PG8_LDA(dst, b, h) do { _Pragma("unroll") for (int m = 0; m < 4; ++m) _Pragma("unroll") for (int k = 0; k < 2; ++k) dst[m][k] = *(const LAS bf16x8*)(lds + PG8_SA(b, h) + aoff + m * 2048 + k * 1024); } while (0)
; #define PG8_LDB(dst, b, h) do { _Pragma("unroll") for (int n = 0; n < 2; ++n) _Pragma("unroll") for (int k = 0; k < 2; ++k) dst[n][k] = *(const LAS bf16x8*)(lds + PG8_SB(b, h) + boff + n * 2048 + k * 1024); } while (0)
; #define PG8_MMA(ai, bj, At, Bt) do { __builtin_amdgcn_s_setprio(1); _Pragma("unroll") for (int m = 0; m < 4; ++m) _Pragma("unroll") for (int n = 0; n < 2; ++n) _Pragma("unroll") for (int k = 0; k < 2; ++k) \
;         acc[ai][bj][m][n] = __builtin_amdgcn_mfma_f32_16x16x32_bf16(Bt[n][k], At[m][k], acc[ai][bj][m][n], 0, 0, 0); __builtin_amdgcn_s_setprio(0); } while (0)
; #define PG8_WAIT_V(n) asm volatile("s_waitcnt vmcnt(" #n ")" ::: "memory")
; #define PG8_WAIT_L(n) asm volatile("s_waitcnt lgkmcnt(" #n ")" ::: "memory")
; #define PG8_BAR __builtin_amdgcn_s_barrier()
; #define PG8_SCHED __builtin_amdgcn_sched_barrier(0)
; template <class Epi>
; DI void gemm_phase(int wv, LAS unsigned char* lds, const GemmD g, const Epi& E) {
;     ...
;             PG8_WAIT_V(6); PG8_BAR; PG8_MMA(1, 1, At, B1); PG8_BAR;
;             PG8_LDB(B0, 1, 0); PG8_SCHED; PG8_LDA(At, 1, 0); PG8_STAGE(PG8_SA(0, 1), a2 + hstepA, voffA);
;             PG8_WAIT_L(8); PG8_BAR; PG8_WAIT_L(0); PG8_MMA(0, 0, At, B0); PG8_BAR; PG8_SCHED;
;             PG8_LDB(B1, 1, 1); PG8_STAGE(PG8_SB(1, 0), b3, voffB);
;             PG8_BAR; PG8_WAIT_L(0); PG8_MMA(0, 1, At, B1); PG8_BAR;
;             PG8_LDA(At, 1, 1); PG8_STAGE(PG8_SA(1, 0), a3, voffA);
;             PG8_BAR; PG8_WAIT_L(0); PG8_MMA(1, 0, At, B0); PG8_BAR; PG8_SCHED;
;             PG8_STAGE(PG8_SB(1, 1), b3 + hstepB, voffB);
;             PG8_WAIT_V(6); PG8_BAR; PG8_MMA(1, 1, At, B1); PG8_BAR;
	s_waitcnt lgkmcnt(0)
	s_waitcnt lgkmcnt(0)
	v_mfma_f32_16x16x32_bf16 v[126:129], v[144:147], v[160:163], v[126:129]
	v_mfma_f32_16x16x32_bf16 v[122:125], v[152:155], v[160:163], v[122:125]
	v_mfma_f32_16x16x32_bf16 v[118:121], v[144:147], v[180:183], v[118:121]
	v_mfma_f32_16x16x32_bf16 v[114:117], v[152:155], v[180:183], v[114:117]
	v_mfma_f32_16x16x32_bf16 v[102:105], v[144:147], v[188:191], v[102:105]
	v_mfma_f32_16x16x32_bf16 v[98:101], v[152:155], v[188:191], v[98:101]
	v_mfma_f32_16x16x32_bf16 v[86:89], v[144:147], v[196:199], v[86:89]
	v_mfma_f32_16x16x32_bf16 v[82:85], v[152:155], v[196:199], v[82:85]
	v_mfma_f32_16x16x32_bf16 v[126:129], v[148:151], v[176:179], v[126:129]
	v_mfma_f32_16x16x32_bf16 v[122:125], v[156:159], v[176:179], v[122:125]
	v_mfma_f32_16x16x32_bf16 v[118:121], v[148:151], v[184:187], v[118:121]
	v_mfma_f32_16x16x32_bf16 v[114:117], v[156:159], v[184:187], v[114:117]
	v_mfma_f32_16x16x32_bf16 v[102:105], v[148:151], v[192:195], v[102:105]
	v_mfma_f32_16x16x32_bf16 v[98:101], v[156:159], v[192:195], v[98:101]
	v_mfma_f32_16x16x32_bf16 v[86:89], v[148:151], v[200:203], v[86:89]
	v_mfma_f32_16x16x32_bf16 v[82:85], v[156:159], v[200:203], v[82:85]
	s_barrier
	s_add_i32 s3, 0, 0x1c000
	s_add_i32 s2, s2, s37
	v_add_u32_e32 v216, s3, v141
	v_lshl_add_u64 v[164:165], v[164:165], 0, s[58:59]
	s_mov_b32 m0, s2
	ds_read_b128 v[204:207], v216
	ds_read_b128 v[208:211], v216 offset:1024
	ds_read_b128 v[212:215], v216 offset:2048
	ds_read_b128 v[216:219], v216 offset:3072
	global_load_lds_dwordx4 v[164:165], off
	s_add_i32 m0, s2, 0x2000
	v_lshl_add_u64 v[164:165], v[168:169], 0, s[58:59]
	global_load_lds_dwordx4 v[164:165], off
	s_barrier
	s_waitcnt lgkmcnt(0)
	s_waitcnt lgkmcnt(0)
	v_mfma_f32_16x16x32_bf16 v[110:113], v[204:207], v[160:163], v[110:113]
	v_mfma_f32_16x16x32_bf16 v[106:109], v[212:215], v[160:163], v[106:109]
	v_mfma_f32_16x16x32_bf16 v[94:97], v[204:207], v[180:183], v[94:97]
	v_mfma_f32_16x16x32_bf16 v[90:93], v[212:215], v[180:183], v[90:93]
	v_mfma_f32_16x16x32_bf16 v[78:81], v[204:207], v[188:191], v[78:81]
	v_mfma_f32_16x16x32_bf16 v[74:77], v[212:215], v[188:191], v[74:77]
	v_mfma_f32_16x16x32_bf16 v[70:73], v[204:207], v[196:199], v[70:73]
	v_mfma_f32_16x16x32_bf16 v[66:69], v[212:215], v[196:199], v[66:69]
	v_mfma_f32_16x16x32_bf16 v[110:113], v[208:211], v[176:179], v[110:113]
	v_mfma_f32_16x16x32_bf16 v[106:109], v[216:219], v[176:179], v[106:109]
	v_mfma_f32_16x16x32_bf16 v[94:97], v[208:211], v[184:187], v[94:97]
	v_mfma_f32_16x16x32_bf16 v[90:93], v[216:219], v[184:187], v[90:93]
	v_mfma_f32_16x16x32_bf16 v[78:81], v[208:211], v[192:195], v[78:81]
	v_mfma_f32_16x16x32_bf16 v[74:77], v[216:219], v[192:195], v[74:77]
	v_mfma_f32_16x16x32_bf16 v[70:73], v[208:211], v[200:203], v[70:73]
	v_mfma_f32_16x16x32_bf16 v[66:69], v[216:219], v[200:203], v[66:69]
	s_mov_b32 m0, s84
	v_lshl_add_u64 v[164:165], v[170:171], 0, s[58:59]
	s_barrier
	ds_read_b128 v[160:163], v143 offset:49152
	ds_read_b128 v[176:179], v143 offset:50176
	ds_read_b128 v[180:183], v143 offset:51200
	ds_read_b128 v[184:187], v143 offset:52224
	ds_read_b128 v[188:191], v143 offset:53248
	ds_read_b128 v[192:195], v143 offset:54272
	ds_read_b128 v[196:199], v143 offset:55296
	ds_read_b128 v[200:203], v143 offset:56320
	global_load_lds_dwordx4 v[164:165], off
	v_lshl_add_u64 v[164:165], v[220:221], 0, s[58:59]
	s_mov_b32 m0, s85
	s_nop 0
	global_load_lds_dwordx4 v[164:165], off
	s_barrier
	s_waitcnt lgkmcnt(0)
	s_waitcnt lgkmcnt(0)
	v_mfma_f32_16x16x32_bf16 v[62:65], v[144:147], v[160:163], v[62:65]
	v_mfma_f32_16x16x32_bf16 v[58:61], v[152:155], v[160:163], v[58:61]
	v_mfma_f32_16x16x32_bf16 v[54:57], v[144:147], v[180:183], v[54:57]
	v_mfma_f32_16x16x32_bf16 v[50:53], v[152:155], v[180:183], v[50:53]
	v_mfma_f32_16x16x32_bf16 v[38:41], v[144:147], v[188:191], v[38:41]
	v_mfma_f32_16x16x32_bf16 v[34:37], v[152:155], v[188:191], v[34:37]
	v_mfma_f32_16x16x32_bf16 v[22:25], v[144:147], v[196:199], v[22:25]
	v_mfma_f32_16x16x32_bf16 v[18:21], v[152:155], v[196:199], v[18:21]
	v_mfma_f32_16x16x32_bf16 v[62:65], v[148:151], v[176:179], v[62:65]
	v_mfma_f32_16x16x32_bf16 v[58:61], v[156:159], v[176:179], v[58:61]
	v_mfma_f32_16x16x32_bf16 v[54:57], v[148:151], v[184:187], v[54:57]
	v_mfma_f32_16x16x32_bf16 v[50:53], v[156:159], v[184:187], v[50:53]
	v_mfma_f32_16x16x32_bf16 v[38:41], v[148:151], v[192:195], v[38:41]
	v_mfma_f32_16x16x32_bf16 v[34:37], v[156:159], v[192:195], v[34:37]
	v_mfma_f32_16x16x32_bf16 v[22:25], v[148:151], v[200:203], v[22:25]
	v_mfma_f32_16x16x32_bf16 v[18:21], v[156:159], v[200:203], v[18:21]
	s_barrier
	s_add_i32 s2, s3, s37
	v_lshl_add_u64 v[144:145], v[222:223], 0, s[58:59]
	s_mov_b32 m0, s2
	s_nop 0
	global_load_lds_dwordx4 v[144:145], off
	s_add_i32 m0, s2, 0x2000
	v_lshl_add_u64 v[144:145], v[224:225], 0, s[58:59]
	global_load_lds_dwordx4 v[144:145], off
	s_waitcnt vmcnt(6)
	s_barrier
	v_mfma_f32_16x16x32_bf16 v[46:49], v[204:207], v[160:163], v[46:49]
	v_mfma_f32_16x16x32_bf16 v[42:45], v[212:215], v[160:163], v[42:45]
	v_mfma_f32_16x16x32_bf16 v[30:33], v[204:207], v[180:183], v[30:33]
	v_mfma_f32_16x16x32_bf16 v[26:29], v[212:215], v[180:183], v[26:29]
	v_mfma_f32_16x16x32_bf16 v[14:17], v[204:207], v[188:191], v[14:17]
	v_mfma_f32_16x16x32_bf16 v[10:13], v[212:215], v[188:191], v[10:13]
	v_mfma_f32_16x16x32_bf16 v[6:9], v[204:207], v[196:199], v[6:9]
	v_mfma_f32_16x16x32_bf16 v[2:5], v[212:215], v[196:199], v[2:5]
	v_mfma_f32_16x16x32_bf16 v[46:49], v[208:211], v[176:179], v[46:49]
	v_mfma_f32_16x16x32_bf16 v[42:45], v[216:219], v[176:179], v[42:45]
	v_mfma_f32_16x16x32_bf16 v[30:33], v[208:211], v[184:187], v[30:33]
	v_mfma_f32_16x16x32_bf16 v[26:29], v[216:219], v[184:187], v[26:29]
	v_mfma_f32_16x16x32_bf16 v[14:17], v[208:211], v[192:195], v[14:17]
	v_mfma_f32_16x16x32_bf16 v[10:13], v[216:219], v[192:195], v[10:13]
	v_mfma_f32_16x16x32_bf16 v[6:9], v[208:211], v[200:203], v[6:9]
	v_mfma_f32_16x16x32_bf16 v[2:5], v[216:219], v[200:203], v[2:5]
	s_add_i32 s95, s95, 2
	s_add_u32 s4, s4, 0x100
	s_addc_u32 s5, s5, 0
	s_add_u32 vcc_hi, vcc_hi, 0x100
	s_addc_u32 s75, s75, 0
	s_cmp_gt_u32 s95, 13
	s_barrier
	s_cbranch_scc0 .LBB0_99

; #define PG8_STAGE(bufoff, gbase, voff) do { _Pragma("unroll") for (int _i = 0; _i < 2; ++_i) \
;         __builtin_amdgcn_global_load_lds((const unsigned*)((const char*)(gbase) + (voff)[_i]), (LAS unsigned*)(lds + (bufoff) + ldsw + _i * 8192), 16, 0, 0); } while (0)
; #define PG8_LDA(dst, b, h) do { _Pragma("unroll") for (int m = 0; m < 4; ++m) _Pragma("unroll") for (int k = 0; k < 2; ++k) dst[m][k] = *(const LAS bf16x8*)(lds + PG8_SA(b, h) + aoff + m * 2048 + k * 1024); } while (0)
; #define PG8_LDB(dst, b, h) do { _Pragma("unroll") for (int n = 0; n < 2; ++n) _Pragma("unroll") for (int k = 0; k < 2; ++k) dst[n][k] = *(const LAS bf16x8*)(lds + PG8_SB(b, h) + boff + n * 2048 + k * 1024); } while (0)
; #define PG8_WAIT_V(n) asm volatile("s_waitcnt vmcnt(" #n ")" ::: "memory")
; #define PG8_WAIT_L(n) asm volatile("s_waitcnt lgkmcnt(" #n ")" ::: "memory")
; #define PG8_BAR __builtin_amdgcn_s_barrier()
; #define PG8_SCHED __builtin_amdgcn_sched_barrier(0)
; template <class Epi>
; DI void gemm_phase(int wv, LAS unsigned char* lds, const GemmD g, const Epi& E) {
;     ...
;         const bool has_next = S.next(ui + 1, nxt);
;         const char* nA = has_next ? (const char*)g.A + (size_t)nxt.pm * 256 * g.lda * 2 : cA; const char* nB = has_next ? (const char*)g.Bt + PG8_BROW(nxt.pn) * (size_t)g.ldb * 2 : cB;
;         for (int t = 0; t < nt; t += 2) {
;             const bool last = (t == nt - 2);
;             const char* a1 = cA + (size_t)(t + 1) * kstep;
;             const char* a2 = last ? nA : cA + (size_t)(t + 2) * kstep; const char* b2 = last ? nB : cB + (size_t)(t + 2) * kstep;
;             const char* a3 = a2 + kstep; const char* b3 = b2 + kstep;
;             PG8_LDB(B0, 0, 0); PG8_SCHED; PG8_LDA(At, 0, 0); PG8_STAGE(PG8_SA(1, 1), a1 + hstepA, voffA);
;             PG8_WAIT_L(8); PG8_BAR; PG8_WAIT_L(0); PG8_MMA(0, 0, At, B0); PG8_BAR; PG8_SCHED;
;             PG8_LDB(B1, 0, 1); PG8_STAGE(PG8_SB(0, 0), b2, voffB);
;             PG8_BAR; PG8_WAIT_L(0); PG8_MMA(0, 1, At, B1); PG8_BAR;
;             PG8_LDA(At, 0, 1); PG8_STAGE(PG8_SA(0, 0), a2, voffA);
;             PG8_BAR; PG8_WAIT_L(0); PG8_MMA(1, 0, At, B0); PG8_BAR; PG8_SCHED;
;             PG8_STAGE(PG8_SB(0, 1), b2 + hstepB, voffB);
;             PG8_WAIT_V(6); PG8_BAR; PG8_MMA(1, 1, At, B1); PG8_BAR;
.LBB0_489:
	s_ashr_i32 s7, s6, 31
	v_cmp_lt_i64_e32 vcc, s[8:9], v[228:229]
	s_lshl_b64 s[8:9], s[6:7], 19
	s_add_u32 s8, s76, s8
	s_addc_u32 s9, s78, s9
	s_and_b64 s[16:17], vcc, exec
	s_cselect_b32 s7, s9, s27
	s_cselect_b32 s13, s8, s26
	s_lshl_b32 s16, s86, 8
	s_ashr_i32 s17, s16, 31
	s_lshl_b64 s[16:17], s[16:17], 11
	s_add_u32 s22, s39, s16
	s_addc_u32 s23, s40, s17
	s_and_b64 s[16:17], vcc, exec
	s_cselect_b32 s16, s23, s29
	s_cselect_b32 s17, s22, s28
	s_add_u32 s26, s26, 0x40080
	s_addc_u32 s27, s27, 0
	s_add_u32 s36, s28, 0x100
	s_addc_u32 s38, s29, 0
	s_mov_b32 s41, -2
	s_add_u32 s2, s26, 0xfffc0080
	s_addc_u32 s3, s27, -1
	s_add_i32 s18, 0, 0x10000
	v_add_u32_e32 v140, s18, v144
	ds_read_b128 v[148:151], v140
	ds_read_b128 v[152:155], v140 offset:1024
	ds_read_b128 v[156:159], v140 offset:2048
	ds_read_b128 v[160:163], v140 offset:3072
	s_cmp_eq_u32 s41, 12
	s_cselect_b32 s31, s7, s3
	s_cselect_b32 s30, s13, s2
	s_cselect_b32 s29, s16, s38
	s_cselect_b32 s28, s17, s36
	v_lshl_add_u64 v[140:141], s[26:27], 0, v[136:137]
	s_add_i32 m0, s25, 0xc000
	ds_read_b128 v[168:171], v146
	ds_read_b128 v[176:179], v146 offset:1024
	ds_read_b128 v[180:183], v146 offset:2048
	ds_read_b128 v[184:187], v146 offset:3072
	ds_read_b128 v[188:191], v146 offset:4096
	ds_read_b128 v[192:195], v146 offset:5120
	ds_read_b128 v[196:199], v146 offset:6144
	ds_read_b128 v[200:203], v146 offset:7168
	global_load_lds_dwordx4 v[140:141], off
	s_add_i32 m0, s25, 0xe000
	v_lshl_add_u64 v[140:141], s[26:27], 0, v[138:139]
	global_load_lds_dwordx4 v[140:141], off
	s_waitcnt lgkmcnt(8)
	s_barrier
	s_waitcnt lgkmcnt(0)
	s_waitcnt lgkmcnt(0)
	v_mfma_f32_16x16x32_bf16 v[126:129], v[148:151], v[168:171], 0
	v_mfma_f32_16x16x32_bf16 v[122:125], v[156:159], v[168:171], 0
	v_mfma_f32_16x16x32_bf16 v[110:113], v[148:151], v[180:183], 0
	v_mfma_f32_16x16x32_bf16 v[106:109], v[156:159], v[180:183], 0
	v_mfma_f32_16x16x32_bf16 v[94:97], v[148:151], v[188:191], 0
	v_mfma_f32_16x16x32_bf16 v[90:93], v[156:159], v[188:191], 0
	v_mfma_f32_16x16x32_bf16 v[78:81], v[148:151], v[196:199], 0
	v_mfma_f32_16x16x32_bf16 v[74:77], v[156:159], v[196:199], 0
	v_mfma_f32_16x16x32_bf16 v[126:129], v[152:155], v[176:179], v[126:129]
	v_mfma_f32_16x16x32_bf16 v[122:125], v[160:163], v[176:179], v[122:125]
	v_mfma_f32_16x16x32_bf16 v[110:113], v[152:155], v[184:187], v[110:113]
	v_mfma_f32_16x16x32_bf16 v[106:109], v[160:163], v[184:187], v[106:109]
	v_mfma_f32_16x16x32_bf16 v[94:97], v[152:155], v[192:195], v[94:97]
	v_mfma_f32_16x16x32_bf16 v[90:93], v[160:163], v[192:195], v[90:93]
	v_mfma_f32_16x16x32_bf16 v[78:81], v[152:155], v[200:203], v[78:81]
	v_mfma_f32_16x16x32_bf16 v[74:77], v[160:163], v[200:203], v[74:77]
	s_barrier
	s_add_i32 s2, 0, 0x14000
	v_add_u32_e32 v140, s2, v144
	s_add_i32 s3, s18, s79
	ds_read_b128 v[204:207], v140
	ds_read_b128 v[208:211], v140 offset:1024
	ds_read_b128 v[212:215], v140 offset:2048
	ds_read_b128 v[216:219], v140 offset:3072
	v_lshl_add_u64 v[140:141], s[28:29], 0, v[0:1]
	s_mov_b32 m0, s3
	v_lshl_add_u64 v[164:165], s[28:29], 0, v[134:135]
	global_load_lds_dwordx4 v[140:141], off
	s_add_i32 m0, s3, 0x2000
	s_nop 0
	global_load_lds_dwordx4 v[164:165], off
	s_barrier
	s_waitcnt lgkmcnt(0)
	s_waitcnt lgkmcnt(0)
	v_mfma_f32_16x16x32_bf16 v[118:121], v[204:207], v[168:171], 0
	v_mfma_f32_16x16x32_bf16 v[114:117], v[212:215], v[168:171], 0
	v_mfma_f32_16x16x32_bf16 v[102:105], v[204:207], v[180:183], 0
	v_mfma_f32_16x16x32_bf16 v[98:101], v[212:215], v[180:183], 0
	v_mfma_f32_16x16x32_bf16 v[86:89], v[204:207], v[188:191], 0
	v_mfma_f32_16x16x32_bf16 v[82:85], v[212:215], v[188:191], 0
	v_mfma_f32_16x16x32_bf16 v[70:73], v[204:207], v[196:199], 0
	v_mfma_f32_16x16x32_bf16 v[66:69], v[212:215], v[196:199], 0
	v_mfma_f32_16x16x32_bf16 v[118:121], v[208:211], v[176:179], v[118:121]
	v_mfma_f32_16x16x32_bf16 v[114:117], v[216:219], v[176:179], v[114:117]
	v_mfma_f32_16x16x32_bf16 v[102:105], v[208:211], v[184:187], v[102:105]
	v_mfma_f32_16x16x32_bf16 v[98:101], v[216:219], v[184:187], v[98:101]
	v_mfma_f32_16x16x32_bf16 v[86:89], v[208:211], v[192:195], v[86:89]
	v_mfma_f32_16x16x32_bf16 v[82:85], v[216:219], v[192:195], v[82:85]
	v_mfma_f32_16x16x32_bf16 v[70:73], v[208:211], v[200:203], v[70:73]
	v_mfma_f32_16x16x32_bf16 v[66:69], v[216:219], v[200:203], v[66:69]
	s_mov_b32 m0, s25
	v_lshl_add_u64 v[220:221], s[30:31], 0, v[130:131]
	s_barrier
	ds_read_b128 v[168:171], v146 offset:16384
	ds_read_b128 v[176:179], v146 offset:17408
	ds_read_b128 v[180:183], v146 offset:18432
	ds_read_b128 v[184:187], v146 offset:19456
	ds_read_b128 v[188:191], v146 offset:20480
	ds_read_b128 v[192:195], v146 offset:21504
	ds_read_b128 v[196:199], v146 offset:22528
	ds_read_b128 v[200:203], v146 offset:23552
	global_load_lds_dwordx4 v[220:221], off
	v_lshl_add_u64 v[222:223], s[30:31], 0, v[132:133]
	s_mov_b32 m0, s80
	s_nop 0
	global_load_lds_dwordx4 v[222:223], off
	s_barrier
	s_waitcnt lgkmcnt(0)
	s_waitcnt lgkmcnt(0)
	v_mfma_f32_16x16x32_bf16 v[62:65], v[148:151], v[168:171], 0
	v_mfma_f32_16x16x32_bf16 v[58:61], v[156:159], v[168:171], 0
	v_mfma_f32_16x16x32_bf16 v[46:49], v[148:151], v[180:183], 0
	v_mfma_f32_16x16x32_bf16 v[42:45], v[156:159], v[180:183], 0
	v_mfma_f32_16x16x32_bf16 v[30:33], v[148:151], v[188:191], 0
	v_mfma_f32_16x16x32_bf16 v[26:29], v[156:159], v[188:191], 0
	v_mfma_f32_16x16x32_bf16 v[14:17], v[148:151], v[196:199], 0
	v_mfma_f32_16x16x32_bf16 v[10:13], v[156:159], v[196:199], 0
	v_mfma_f32_16x16x32_bf16 v[62:65], v[152:155], v[176:179], v[62:65]
	v_mfma_f32_16x16x32_bf16 v[58:61], v[160:163], v[176:179], v[58:61]
	v_mfma_f32_16x16x32_bf16 v[46:49], v[152:155], v[184:187], v[46:49]
	v_mfma_f32_16x16x32_bf16 v[42:45], v[160:163], v[184:187], v[42:45]
	v_mfma_f32_16x16x32_bf16 v[30:33], v[152:155], v[192:195], v[30:33]
	v_mfma_f32_16x16x32_bf16 v[26:29], v[160:163], v[192:195], v[26:29]
	v_mfma_f32_16x16x32_bf16 v[14:17], v[152:155], v[200:203], v[14:17]
	v_mfma_f32_16x16x32_bf16 v[10:13], v[160:163], v[200:203], v[10:13]
	s_barrier
; #define PG8_STAGE(bufoff, gbase, voff) do { _Pragma("unroll") for (int _i = 0; _i < 2; ++_i) \
;         __builtin_amdgcn_global_load_lds((const unsigned*)((const char*)(gbase) + (voff)[_i]), (LAS unsigned*)(lds + (bufoff) + ldsw + _i * 8192), 16, 0, 0); } while (0)
; #define PG8_LDA(dst, b, h) do { _Pragma("unroll") for (int m = 0; m < 4; ++m) _Pragma("unroll") for (int k = 0; k < 2; ++k) dst[m][k] = *(const LAS bf16x8*)(lds + PG8_SA(b, h) + aoff + m * 2048 + k * 1024); } while (0)
; #define PG8_LDB(dst, b, h) do { _Pragma("unroll") for (int n = 0; n < 2; ++n) _Pragma("unroll") for (int k = 0; k < 2; ++k) dst[n][k] = *(const LAS bf16x8*)(lds + PG8_SB(b, h) + boff + n * 2048 + k * 1024); } while (0)
; #define PG8_MMA(ai, bj, At, Bt) do { __builtin_amdgcn_s_setprio(1); _Pragma("unroll") for (int m = 0; m < 4; ++m) _Pragma("unroll") for (int n = 0; n < 2; ++n) _Pragma("unroll") for (int k = 0; k < 2; ++k) \
;         acc[ai][bj][m][n] = __builtin_amdgcn_mfma_f32_16x16x32_bf16(Bt[n][k], At[m][k], acc[ai][bj][m][n], 0, 0, 0); __builtin_amdgcn_s_setprio(0); } while (0)
; #define PG8_WAIT_V(n) asm volatile("s_waitcnt vmcnt(" #n ")" ::: "memory")
; #define PG8_WAIT_L(n) asm volatile("s_waitcnt lgkmcnt(" #n ")" ::: "memory")
; #define PG8_BAR __builtin_amdgcn_s_barrier()
; #define PG8_SCHED __builtin_amdgcn_sched_barrier(0)
; template <class Epi>
; DI void gemm_phase(int wv, LAS unsigned char* lds, const GemmD g, const Epi& E) {
;     ...
;             PG8_BAR; PG8_WAIT_L(0); PG8_MMA(1, 0, At, B0); PG8_BAR; PG8_SCHED;
;             PG8_STAGE(PG8_SB(0, 1), b2 + hstepB, voffB);
;             PG8_WAIT_V(6); PG8_BAR; PG8_MMA(1, 1, At, B1); PG8_BAR;
;             PG8_LDB(B0, 1, 0); PG8_SCHED; PG8_LDA(At, 1, 0); PG8_STAGE(PG8_SA(0, 1), a2 + hstepA, voffA);
;             PG8_WAIT_L(8); PG8_BAR; PG8_WAIT_L(0); PG8_MMA(0, 0, At, B0); PG8_BAR; PG8_SCHED;
;             PG8_LDB(B1, 1, 1); PG8_STAGE(PG8_SB(1, 0), b3, voffB);
;             PG8_BAR; PG8_WAIT_L(0); PG8_MMA(0, 1, At, B1); PG8_BAR;
;             PG8_LDA(At, 1, 1); PG8_STAGE(PG8_SA(1, 0), a3, voffA);
;             PG8_BAR; PG8_WAIT_L(0); PG8_MMA(1, 0, At, B0); PG8_BAR; PG8_SCHED;
	s_add_u32 s18, s28, 0x40000
	s_addc_u32 s19, s29, 0
	s_add_i32 s2, s2, s79
	v_lshl_add_u64 v[148:149], s[18:19], 0, v[0:1]
	s_mov_b32 m0, s2
	s_nop 0
	global_load_lds_dwordx4 v[148:149], off
	s_add_i32 m0, s2, 0x2000
	v_lshl_add_u64 v[148:149], s[18:19], 0, v[134:135]
	global_load_lds_dwordx4 v[148:149], off
	s_waitcnt vmcnt(6)
	s_barrier
	v_mfma_f32_16x16x32_bf16 v[54:57], v[204:207], v[168:171], 0
	v_mfma_f32_16x16x32_bf16 v[50:53], v[212:215], v[168:171], 0
	v_mfma_f32_16x16x32_bf16 v[38:41], v[204:207], v[180:183], 0
	v_mfma_f32_16x16x32_bf16 v[34:37], v[212:215], v[180:183], 0
	v_mfma_f32_16x16x32_bf16 v[22:25], v[204:207], v[188:191], 0
	v_mfma_f32_16x16x32_bf16 v[18:21], v[212:215], v[188:191], 0
	v_mfma_f32_16x16x32_bf16 v[6:9], v[204:207], v[196:199], 0
	v_mfma_f32_16x16x32_bf16 v[2:5], v[212:215], v[196:199], 0
	v_mfma_f32_16x16x32_bf16 v[54:57], v[208:211], v[176:179], v[54:57]
	v_mfma_f32_16x16x32_bf16 v[50:53], v[216:219], v[176:179], v[50:53]
	v_mfma_f32_16x16x32_bf16 v[38:41], v[208:211], v[184:187], v[38:41]
	v_mfma_f32_16x16x32_bf16 v[34:37], v[216:219], v[184:187], v[34:37]
	v_mfma_f32_16x16x32_bf16 v[22:25], v[208:211], v[192:195], v[22:25]
	v_mfma_f32_16x16x32_bf16 v[18:21], v[216:219], v[192:195], v[18:21]
	v_mfma_f32_16x16x32_bf16 v[6:9], v[208:211], v[200:203], v[6:9]
	v_mfma_f32_16x16x32_bf16 v[2:5], v[216:219], v[200:203], v[2:5]
	s_add_i32 s2, 0, 0x18000
	v_add_u32_e32 v147, s2, v144
	s_barrier
	ds_read_b128 v[148:151], v147
	ds_read_b128 v[152:155], v147 offset:1024
	ds_read_b128 v[156:159], v147 offset:2048
	ds_read_b128 v[160:163], v147 offset:3072
	s_add_u32 s18, s30, 0x40000
	s_addc_u32 s19, s31, 0
	s_mov_b32 m0, s81
	v_lshl_add_u64 v[204:205], s[18:19], 0, v[130:131]
	ds_read_b128 v[168:171], v146 offset:32768
	ds_read_b128 v[176:179], v146 offset:33792
	ds_read_b128 v[180:183], v146 offset:34816
	ds_read_b128 v[184:187], v146 offset:35840
	ds_read_b128 v[188:191], v146 offset:36864
	ds_read_b128 v[192:195], v146 offset:37888
	ds_read_b128 v[196:199], v146 offset:38912
	ds_read_b128 v[200:203], v146 offset:39936
	global_load_lds_dwordx4 v[204:205], off
	v_lshl_add_u64 v[204:205], s[18:19], 0, v[132:133]
	s_mov_b32 m0, s82
	s_nop 0
	global_load_lds_dwordx4 v[204:205], off
	s_waitcnt lgkmcnt(8)
	s_barrier
	s_waitcnt lgkmcnt(0)
	s_waitcnt lgkmcnt(0)
	v_mfma_f32_16x16x32_bf16 v[126:129], v[148:151], v[168:171], v[126:129]
	v_mfma_f32_16x16x32_bf16 v[122:125], v[156:159], v[168:171], v[122:125]
	v_mfma_f32_16x16x32_bf16 v[110:113], v[148:151], v[180:183], v[110:113]
	v_mfma_f32_16x16x32_bf16 v[106:109], v[156:159], v[180:183], v[106:109]
	v_mfma_f32_16x16x32_bf16 v[94:97], v[148:151], v[188:191], v[94:97]
	v_mfma_f32_16x16x32_bf16 v[90:93], v[156:159], v[188:191], v[90:93]
	v_mfma_f32_16x16x32_bf16 v[78:81], v[148:151], v[196:199], v[78:81]
	v_mfma_f32_16x16x32_bf16 v[74:77], v[156:159], v[196:199], v[74:77]
	v_mfma_f32_16x16x32_bf16 v[126:129], v[152:155], v[176:179], v[126:129]
	v_mfma_f32_16x16x32_bf16 v[122:125], v[160:163], v[176:179], v[122:125]
	v_mfma_f32_16x16x32_bf16 v[110:113], v[152:155], v[184:187], v[110:113]
	v_mfma_f32_16x16x32_bf16 v[106:109], v[160:163], v[184:187], v[106:109]
	v_mfma_f32_16x16x32_bf16 v[94:97], v[152:155], v[192:195], v[94:97]
	v_mfma_f32_16x16x32_bf16 v[90:93], v[160:163], v[192:195], v[90:93]
	v_mfma_f32_16x16x32_bf16 v[78:81], v[152:155], v[200:203], v[78:81]
	v_mfma_f32_16x16x32_bf16 v[74:77], v[160:163], v[200:203], v[74:77]
	s_barrier
	s_add_i32 s3, 0, 0x1c000
	s_add_i32 s2, s2, s79
	v_add_u32_e32 v147, s3, v144
	v_lshl_add_u64 v[140:141], v[140:141], 0, s[58:59]
	s_mov_b32 m0, s2
	ds_read_b128 v[204:207], v147
	ds_read_b128 v[208:211], v147 offset:1024
	ds_read_b128 v[212:215], v147 offset:2048
	ds_read_b128 v[216:219], v147 offset:3072
	global_load_lds_dwordx4 v[140:141], off
	s_add_i32 m0, s2, 0x2000
	v_lshl_add_u64 v[140:141], v[164:165], 0, s[58:59]
	global_load_lds_dwordx4 v[140:141], off
	s_barrier
	s_waitcnt lgkmcnt(0)
	s_waitcnt lgkmcnt(0)
	v_mfma_f32_16x16x32_bf16 v[118:121], v[204:207], v[168:171], v[118:121]
	v_mfma_f32_16x16x32_bf16 v[114:117], v[212:215], v[168:171], v[114:117]
	v_mfma_f32_16x16x32_bf16 v[102:105], v[204:207], v[180:183], v[102:105]
	v_mfma_f32_16x16x32_bf16 v[98:101], v[212:215], v[180:183], v[98:101]
	v_mfma_f32_16x16x32_bf16 v[86:89], v[204:207], v[188:191], v[86:89]
	v_mfma_f32_16x16x32_bf16 v[82:85], v[212:215], v[188:191], v[82:85]
	v_mfma_f32_16x16x32_bf16 v[70:73], v[204:207], v[196:199], v[70:73]
	v_mfma_f32_16x16x32_bf16 v[66:69], v[212:215], v[196:199], v[66:69]
	v_mfma_f32_16x16x32_bf16 v[118:121], v[208:211], v[176:179], v[118:121]
	v_mfma_f32_16x16x32_bf16 v[114:117], v[216:219], v[176:179], v[114:117]
	v_mfma_f32_16x16x32_bf16 v[102:105], v[208:211], v[184:187], v[102:105]
	v_mfma_f32_16x16x32_bf16 v[98:101], v[216:219], v[184:187], v[98:101]
	v_mfma_f32_16x16x32_bf16 v[86:89], v[208:211], v[192:195], v[86:89]
	v_mfma_f32_16x16x32_bf16 v[82:85], v[216:219], v[192:195], v[82:85]
	v_mfma_f32_16x16x32_bf16 v[70:73], v[208:211], v[200:203], v[70:73]
	v_mfma_f32_16x16x32_bf16 v[66:69], v[216:219], v[200:203], v[66:69]
	s_mov_b32 m0, s83
	v_lshl_add_u64 v[140:141], v[220:221], 0, s[58:59]
	s_barrier
	ds_read_b128 v[168:171], v146 offset:49152
	ds_read_b128 v[176:179], v146 offset:50176
	ds_read_b128 v[180:183], v146 offset:51200
	ds_read_b128 v[184:187], v146 offset:52224
	ds_read_b128 v[188:191], v146 offset:53248
	ds_read_b128 v[192:195], v146 offset:54272
	ds_read_b128 v[196:199], v146 offset:55296
	ds_read_b128 v[200:203], v146 offset:56320
	global_load_lds_dwordx4 v[140:141], off
	v_lshl_add_u64 v[140:141], v[222:223], 0, s[58:59]
	s_mov_b32 m0, s84
	s_nop 0
	global_load_lds_dwordx4 v[140:141], off
	s_barrier
; #define PG8_STAGE(bufoff, gbase, voff) do { _Pragma("unroll") for (int _i = 0; _i < 2; ++_i) \
;         __builtin_amdgcn_global_load_lds((const unsigned*)((const char*)(gbase) + (voff)[_i]), (LAS unsigned*)(lds + (bufoff) + ldsw + _i * 8192), 16, 0, 0); } while (0)
; #define PG8_LDA(dst, b, h) do { _Pragma("unroll") for (int m = 0; m < 4; ++m) _Pragma("unroll") for (int k = 0; k < 2; ++k) dst[m][k] = *(const LAS bf16x8*)(lds + PG8_SA(b, h) + aoff + m * 2048 + k * 1024); } while (0)
; #define PG8_LDB(dst, b, h) do { _Pragma("unroll") for (int n = 0; n < 2; ++n) _Pragma("unroll") for (int k = 0; k < 2; ++k) dst[n][k] = *(const LAS bf16x8*)(lds + PG8_SB(b, h) + boff + n * 2048 + k * 1024); } while (0)
; #define PG8_MMA(ai, bj, At, Bt) do { __builtin_amdgcn_s_setprio(1); _Pragma("unroll") for (int m = 0; m < 4; ++m) _Pragma("unroll") for (int n = 0; n < 2; ++n) _Pragma("unroll") for (int k = 0; k < 2; ++k) \
;         acc[ai][bj][m][n] = __builtin_amdgcn_mfma_f32_16x16x32_bf16(Bt[n][k], At[m][k], acc[ai][bj][m][n], 0, 0, 0); __builtin_amdgcn_s_setprio(0); } while (0)
; #define PG8_WAIT_V(n) asm volatile("s_waitcnt vmcnt(" #n ")" ::: "memory")
; #define PG8_WAIT_L(n) asm volatile("s_waitcnt lgkmcnt(" #n ")" ::: "memory")
; #define PG8_BAR __builtin_amdgcn_s_barrier()
; #define PG8_SCHED __builtin_amdgcn_sched_barrier(0)
; template <class Epi>
; DI void gemm_phase(int wv, LAS unsigned char* lds, const GemmD g, const Epi& E) {
;     ...
;         for (int t = 0; t < nt; t += 2) {
;             const bool last = (t == nt - 2);
;             const char* a1 = cA + (size_t)(t + 1) * kstep;
;             const char* a2 = last ? nA : cA + (size_t)(t + 2) * kstep; const char* b2 = last ? nB : cB + (size_t)(t + 2) * kstep;
;             const char* a3 = a2 + kstep; const char* b3 = b2 + kstep;
;             PG8_LDB(B0, 0, 0); PG8_SCHED; PG8_LDA(At, 0, 0); PG8_STAGE(PG8_SA(1, 1), a1 + hstepA, voffA);
;             PG8_WAIT_L(8); PG8_BAR; PG8_WAIT_L(0); PG8_MMA(0, 0, At, B0); PG8_BAR; PG8_SCHED;
;     ...
;             PG8_BAR; PG8_WAIT_L(0); PG8_MMA(1, 0, At, B0); PG8_BAR; PG8_SCHED;
;             PG8_STAGE(PG8_SB(1, 1), b3 + hstepB, voffB);
;             PG8_WAIT_V(6); PG8_BAR; PG8_MMA(1, 1, At, B1); PG8_BAR;
	s_waitcnt lgkmcnt(0)
	s_waitcnt lgkmcnt(0)
	v_mfma_f32_16x16x32_bf16 v[62:65], v[148:151], v[168:171], v[62:65]
	v_mfma_f32_16x16x32_bf16 v[58:61], v[156:159], v[168:171], v[58:61]
	v_mfma_f32_16x16x32_bf16 v[46:49], v[148:151], v[180:183], v[46:49]
	v_mfma_f32_16x16x32_bf16 v[42:45], v[156:159], v[180:183], v[42:45]
	v_mfma_f32_16x16x32_bf16 v[30:33], v[148:151], v[188:191], v[30:33]
	v_mfma_f32_16x16x32_bf16 v[26:29], v[156:159], v[188:191], v[26:29]
	v_mfma_f32_16x16x32_bf16 v[14:17], v[148:151], v[196:199], v[14:17]
	v_mfma_f32_16x16x32_bf16 v[10:13], v[156:159], v[196:199], v[10:13]
	v_mfma_f32_16x16x32_bf16 v[62:65], v[152:155], v[176:179], v[62:65]
	v_mfma_f32_16x16x32_bf16 v[58:61], v[160:163], v[176:179], v[58:61]
	v_mfma_f32_16x16x32_bf16 v[46:49], v[152:155], v[184:187], v[46:49]
	v_mfma_f32_16x16x32_bf16 v[42:45], v[160:163], v[184:187], v[42:45]
	v_mfma_f32_16x16x32_bf16 v[30:33], v[152:155], v[192:195], v[30:33]
	v_mfma_f32_16x16x32_bf16 v[26:29], v[160:163], v[192:195], v[26:29]
	v_mfma_f32_16x16x32_bf16 v[14:17], v[152:155], v[200:203], v[14:17]
	v_mfma_f32_16x16x32_bf16 v[10:13], v[160:163], v[200:203], v[10:13]
	s_barrier
	s_add_u32 s18, s28, 0x40080
	s_addc_u32 s19, s29, 0
	s_add_i32 s2, s3, s79
	v_lshl_add_u64 v[140:141], s[18:19], 0, v[0:1]
	s_mov_b32 m0, s2
	s_nop 0
	global_load_lds_dwordx4 v[140:141], off
	s_add_i32 m0, s2, 0x2000
	v_lshl_add_u64 v[140:141], s[18:19], 0, v[134:135]
	global_load_lds_dwordx4 v[140:141], off
	s_waitcnt vmcnt(6)
	s_barrier
	v_mfma_f32_16x16x32_bf16 v[54:57], v[204:207], v[168:171], v[54:57]
	v_mfma_f32_16x16x32_bf16 v[50:53], v[212:215], v[168:171], v[50:53]
	v_mfma_f32_16x16x32_bf16 v[38:41], v[204:207], v[180:183], v[38:41]
	v_mfma_f32_16x16x32_bf16 v[34:37], v[212:215], v[180:183], v[34:37]
	v_mfma_f32_16x16x32_bf16 v[22:25], v[204:207], v[188:191], v[22:25]
	v_mfma_f32_16x16x32_bf16 v[18:21], v[212:215], v[188:191], v[18:21]
	v_mfma_f32_16x16x32_bf16 v[6:9], v[204:207], v[196:199], v[6:9]
	v_mfma_f32_16x16x32_bf16 v[2:5], v[212:215], v[196:199], v[2:5]
	v_mfma_f32_16x16x32_bf16 v[54:57], v[208:211], v[176:179], v[54:57]
	v_mfma_f32_16x16x32_bf16 v[50:53], v[216:219], v[176:179], v[50:53]
	v_mfma_f32_16x16x32_bf16 v[38:41], v[208:211], v[184:187], v[38:41]
	v_mfma_f32_16x16x32_bf16 v[34:37], v[216:219], v[184:187], v[34:37]
	v_mfma_f32_16x16x32_bf16 v[22:25], v[208:211], v[192:195], v[22:25]
	v_mfma_f32_16x16x32_bf16 v[18:21], v[216:219], v[192:195], v[18:21]
	v_mfma_f32_16x16x32_bf16 v[6:9], v[208:211], v[200:203], v[6:9]
	v_mfma_f32_16x16x32_bf16 v[2:5], v[216:219], v[200:203], v[2:5]
	s_add_i32 s41, s41, 2
	s_add_u32 s26, s26, 0x100
	s_addc_u32 s27, s27, 0
	s_add_u32 s36, s36, 0x100
	s_addc_u32 s38, s38, 0
	s_cmp_gt_u32 s41, 13
	s_barrier
	s_cbranch_scc0 .LBB0_490
	s_branch .Lgemm_epi_b
	.p2align 6
.LBB0_490:
	s_add_u32 s2, s26, 0xfffc0080
	s_addc_u32 s3, s27, -1
	s_add_i32 s18, 0, 0x10000
	v_add_u32_e32 v140, s18, v144
	ds_read_b128 v[148:151], v140
	ds_read_b128 v[152:155], v140 offset:1024
	ds_read_b128 v[156:159], v140 offset:2048
	ds_read_b128 v[160:163], v140 offset:3072
	s_cmp_eq_u32 s41, 12
	s_cselect_b32 s31, s7, s3
	s_cselect_b32 s30, s13, s2
	s_cselect_b32 s29, s16, s38
	s_cselect_b32 s28, s17, s36
	v_lshl_add_u64 v[140:141], s[26:27], 0, v[136:137]
	s_add_i32 m0, s25, 0xc000
	ds_read_b128 v[168:171], v146
	ds_read_b128 v[176:179], v146 offset:1024
	ds_read_b128 v[180:183], v146 offset:2048
	ds_read_b128 v[184:187], v146 offset:3072
	ds_read_b128 v[188:191], v146 offset:4096
	ds_read_b128 v[192:195], v146 offset:5120
	ds_read_b128 v[196:199], v146 offset:6144
	ds_read_b128 v[200:203], v146 offset:7168
	global_load_lds_dwordx4 v[140:141], off
	s_add_i32 m0, s25, 0xe000
	v_lshl_add_u64 v[140:141], s[26:27], 0, v[138:139]
	global_load_lds_dwordx4 v[140:141], off
	s_waitcnt lgkmcnt(8)
	s_barrier
	s_waitcnt lgkmcnt(0)
	s_waitcnt lgkmcnt(0)
	v_mfma_f32_16x16x32_bf16 v[126:129], v[148:151], v[168:171], v[126:129]
	v_mfma_f32_16x16x32_bf16 v[122:125], v[156:159], v[168:171], v[122:125]
	v_mfma_f32_16x16x32_bf16 v[110:113], v[148:151], v[180:183], v[110:113]
	v_mfma_f32_16x16x32_bf16 v[106:109], v[156:159], v[180:183], v[106:109]
	v_mfma_f32_16x16x32_bf16 v[94:97], v[148:151], v[188:191], v[94:97]
	v_mfma_f32_16x16x32_bf16 v[90:93], v[156:159], v[188:191], v[90:93]
	v_mfma_f32_16x16x32_bf16 v[78:81], v[148:151], v[196:199], v[78:81]
	v_mfma_f32_16x16x32_bf16 v[74:77], v[156:159], v[196:199], v[74:77]
	v_mfma_f32_16x16x32_bf16 v[126:129], v[152:155], v[176:179], v[126:129]
	v_mfma_f32_16x16x32_bf16 v[122:125], v[160:163], v[176:179], v[122:125]
	v_mfma_f32_16x16x32_bf16 v[110:113], v[152:155], v[184:187], v[110:113]
	v_mfma_f32_16x16x32_bf16 v[106:109], v[160:163], v[184:187], v[106:109]
	v_mfma_f32_16x16x32_bf16 v[94:97], v[152:155], v[192:195], v[94:97]
	v_mfma_f32_16x16x32_bf16 v[90:93], v[160:163], v[192:195], v[90:93]
	v_mfma_f32_16x16x32_bf16 v[78:81], v[152:155], v[200:203], v[78:81]
	v_mfma_f32_16x16x32_bf16 v[74:77], v[160:163], v[200:203], v[74:77]
	s_barrier
	s_add_i32 s2, 0, 0x14000
	v_add_u32_e32 v140, s2, v144
	s_add_i32 s3, s18, s79
	ds_read_b128 v[204:207], v140
	ds_read_b128 v[208:211], v140 offset:1024
	ds_read_b128 v[212:215], v140 offset:2048
	ds_read_b128 v[216:219], v140 offset:3072
	v_lshl_add_u64 v[140:141], s[28:29], 0, v[0:1]
	s_mov_b32 m0, s3
	v_lshl_add_u64 v[164:165], s[28:29], 0, v[134:135]
	global_load_lds_dwordx4 v[140:141], off
	s_add_i32 m0, s3, 0x2000
	s_nop 0
	global_load_lds_dwordx4 v[164:165], off
	s_barrier
; #define PG8_STAGE(bufoff, gbase, voff) do { _Pragma("unroll") for (int _i = 0; _i < 2; ++_i) \
;         __builtin_amdgcn_global_load_lds((const unsigned*)((const char*)(gbase) + (voff)[_i]), (LAS unsigned*)(lds + (bufoff) + ldsw + _i * 8192), 16, 0, 0); } while (0)
; #define PG8_LDA(dst, b, h) do { _Pragma("unroll") for (int m = 0; m < 4; ++m) _Pragma("unroll") for (int k = 0; k < 2; ++k) dst[m][k] = *(const LAS bf16x8*)(lds + PG8_SA(b, h) + aoff + m * 2048 + k * 1024); } while (0)
; #define PG8_LDB(dst, b, h) do { _Pragma("unroll") for (int n = 0; n < 2; ++n) _Pragma("unroll") for (int k = 0; k < 2; ++k) dst[n][k] = *(const LAS bf16x8*)(lds + PG8_SB(b, h) + boff + n * 2048 + k * 1024); } while (0)
; #define PG8_MMA(ai, bj, At, Bt) do { __builtin_amdgcn_s_setprio(1); _Pragma("unroll") for (int m = 0; m < 4; ++m) _Pragma("unroll") for (int n = 0; n < 2; ++n) _Pragma("unroll") for (int k = 0; k < 2; ++k) \
;         acc[ai][bj][m][n] = __builtin_amdgcn_mfma_f32_16x16x32_bf16(Bt[n][k], At[m][k], acc[ai][bj][m][n], 0, 0, 0); __builtin_amdgcn_s_setprio(0); } while (0)
; #define PG8_WAIT_V(n) asm volatile("s_waitcnt vmcnt(" #n ")" ::: "memory")
; #define PG8_WAIT_L(n) asm volatile("s_waitcnt lgkmcnt(" #n ")" ::: "memory")
; #define PG8_BAR __builtin_amdgcn_s_barrier()
; #define PG8_SCHED __builtin_amdgcn_sched_barrier(0)
; template <class Epi>
; DI void gemm_phase(int wv, LAS unsigned char* lds, const GemmD g, const Epi& E) {
;     ...
;             PG8_WAIT_L(8); PG8_BAR; PG8_WAIT_L(0); PG8_MMA(0, 0, At, B0); PG8_BAR; PG8_SCHED;
;             PG8_LDB(B1, 0, 1); PG8_STAGE(PG8_SB(0, 0), b2, voffB);
;             PG8_BAR; PG8_WAIT_L(0); PG8_MMA(0, 1, At, B1); PG8_BAR;
;             PG8_LDA(At, 0, 1); PG8_STAGE(PG8_SA(0, 0), a2, voffA);
;             PG8_BAR; PG8_WAIT_L(0); PG8_MMA(1, 0, At, B0); PG8_BAR; PG8_SCHED;
;             PG8_STAGE(PG8_SB(0, 1), b2 + hstepB, voffB);
;             PG8_WAIT_V(6); PG8_BAR; PG8_MMA(1, 1, At, B1); PG8_BAR;
;             PG8_LDB(B0, 1, 0); PG8_SCHED; PG8_LDA(At, 1, 0); PG8_STAGE(PG8_SA(0, 1), a2 + hstepA, voffA);
;             PG8_WAIT_L(8); PG8_BAR; PG8_WAIT_L(0); PG8_MMA(0, 0, At, B0); PG8_BAR; PG8_SCHED;
;             PG8_LDB(B1, 1, 1); PG8_STAGE(PG8_SB(1, 0), b3, voffB);
;             PG8_BAR; PG8_WAIT_L(0); PG8_MMA(0, 1, At, B1); PG8_BAR;
	s_waitcnt lgkmcnt(0)
	s_waitcnt lgkmcnt(0)
	v_mfma_f32_16x16x32_bf16 v[118:121], v[204:207], v[168:171], v[118:121]
	v_mfma_f32_16x16x32_bf16 v[114:117], v[212:215], v[168:171], v[114:117]
	v_mfma_f32_16x16x32_bf16 v[102:105], v[204:207], v[180:183], v[102:105]
	v_mfma_f32_16x16x32_bf16 v[98:101], v[212:215], v[180:183], v[98:101]
	v_mfma_f32_16x16x32_bf16 v[86:89], v[204:207], v[188:191], v[86:89]
	v_mfma_f32_16x16x32_bf16 v[82:85], v[212:215], v[188:191], v[82:85]
	v_mfma_f32_16x16x32_bf16 v[70:73], v[204:207], v[196:199], v[70:73]
	v_mfma_f32_16x16x32_bf16 v[66:69], v[212:215], v[196:199], v[66:69]
	v_mfma_f32_16x16x32_bf16 v[118:121], v[208:211], v[176:179], v[118:121]
	v_mfma_f32_16x16x32_bf16 v[114:117], v[216:219], v[176:179], v[114:117]
	v_mfma_f32_16x16x32_bf16 v[102:105], v[208:211], v[184:187], v[102:105]
	v_mfma_f32_16x16x32_bf16 v[98:101], v[216:219], v[184:187], v[98:101]
	v_mfma_f32_16x16x32_bf16 v[86:89], v[208:211], v[192:195], v[86:89]
	v_mfma_f32_16x16x32_bf16 v[82:85], v[216:219], v[192:195], v[82:85]
	v_mfma_f32_16x16x32_bf16 v[70:73], v[208:211], v[200:203], v[70:73]
	v_mfma_f32_16x16x32_bf16 v[66:69], v[216:219], v[200:203], v[66:69]
	s_mov_b32 m0, s25
	v_lshl_add_u64 v[220:221], s[30:31], 0, v[130:131]
	s_barrier
	ds_read_b128 v[168:171], v146 offset:16384
	ds_read_b128 v[176:179], v146 offset:17408
	ds_read_b128 v[180:183], v146 offset:18432
	ds_read_b128 v[184:187], v146 offset:19456
	ds_read_b128 v[188:191], v146 offset:20480
	ds_read_b128 v[192:195], v146 offset:21504
	ds_read_b128 v[196:199], v146 offset:22528
	ds_read_b128 v[200:203], v146 offset:23552
	global_load_lds_dwordx4 v[220:221], off
	v_lshl_add_u64 v[222:223], s[30:31], 0, v[132:133]
	s_mov_b32 m0, s80
	s_nop 0
	global_load_lds_dwordx4 v[222:223], off
	s_barrier
	s_waitcnt lgkmcnt(0)
	s_waitcnt lgkmcnt(0)
	v_mfma_f32_16x16x32_bf16 v[62:65], v[148:151], v[168:171], v[62:65]
	v_mfma_f32_16x16x32_bf16 v[58:61], v[156:159], v[168:171], v[58:61]
	v_mfma_f32_16x16x32_bf16 v[46:49], v[148:151], v[180:183], v[46:49]
	v_mfma_f32_16x16x32_bf16 v[42:45], v[156:159], v[180:183], v[42:45]
	v_mfma_f32_16x16x32_bf16 v[30:33], v[148:151], v[188:191], v[30:33]
	v_mfma_f32_16x16x32_bf16 v[26:29], v[156:159], v[188:191], v[26:29]
	v_mfma_f32_16x16x32_bf16 v[14:17], v[148:151], v[196:199], v[14:17]
	v_mfma_f32_16x16x32_bf16 v[10:13], v[156:159], v[196:199], v[10:13]
	v_mfma_f32_16x16x32_bf16 v[62:65], v[152:155], v[176:179], v[62:65]
	v_mfma_f32_16x16x32_bf16 v[58:61], v[160:163], v[176:179], v[58:61]
	v_mfma_f32_16x16x32_bf16 v[46:49], v[152:155], v[184:187], v[46:49]
	v_mfma_f32_16x16x32_bf16 v[42:45], v[160:163], v[184:187], v[42:45]
	v_mfma_f32_16x16x32_bf16 v[30:33], v[152:155], v[192:195], v[30:33]
	v_mfma_f32_16x16x32_bf16 v[26:29], v[160:163], v[192:195], v[26:29]
	v_mfma_f32_16x16x32_bf16 v[14:17], v[152:155], v[200:203], v[14:17]
	v_mfma_f32_16x16x32_bf16 v[10:13], v[160:163], v[200:203], v[10:13]
	s_barrier
	s_add_u32 s18, s28, 0x40000
	s_addc_u32 s19, s29, 0
	s_add_i32 s2, s2, s79
	v_lshl_add_u64 v[148:149], s[18:19], 0, v[0:1]
	s_mov_b32 m0, s2
	s_nop 0
	global_load_lds_dwordx4 v[148:149], off
	s_add_i32 m0, s2, 0x2000
	v_lshl_add_u64 v[148:149], s[18:19], 0, v[134:135]
	global_load_lds_dwordx4 v[148:149], off
	s_waitcnt vmcnt(6)
	s_barrier
	v_mfma_f32_16x16x32_bf16 v[54:57], v[204:207], v[168:171], v[54:57]
	v_mfma_f32_16x16x32_bf16 v[50:53], v[212:215], v[168:171], v[50:53]
	v_mfma_f32_16x16x32_bf16 v[38:41], v[204:207], v[180:183], v[38:41]
	v_mfma_f32_16x16x32_bf16 v[34:37], v[212:215], v[180:183], v[34:37]
	v_mfma_f32_16x16x32_bf16 v[22:25], v[204:207], v[188:191], v[22:25]
	v_mfma_f32_16x16x32_bf16 v[18:21], v[212:215], v[188:191], v[18:21]
	v_mfma_f32_16x16x32_bf16 v[6:9], v[204:207], v[196:199], v[6:9]
	v_mfma_f32_16x16x32_bf16 v[2:5], v[212:215], v[196:199], v[2:5]
	v_mfma_f32_16x16x32_bf16 v[54:57], v[208:211], v[176:179], v[54:57]
	v_mfma_f32_16x16x32_bf16 v[50:53], v[216:219], v[176:179], v[50:53]
	v_mfma_f32_16x16x32_bf16 v[38:41], v[208:211], v[184:187], v[38:41]
	v_mfma_f32_16x16x32_bf16 v[34:37], v[216:219], v[184:187], v[34:37]
	v_mfma_f32_16x16x32_bf16 v[22:25], v[208:211], v[192:195], v[22:25]
	v_mfma_f32_16x16x32_bf16 v[18:21], v[216:219], v[192:195], v[18:21]
	v_mfma_f32_16x16x32_bf16 v[6:9], v[208:211], v[200:203], v[6:9]
	v_mfma_f32_16x16x32_bf16 v[2:5], v[216:219], v[200:203], v[2:5]
	s_add_i32 s2, 0, 0x18000
	v_add_u32_e32 v147, s2, v144
	s_barrier
	ds_read_b128 v[148:151], v147
	ds_read_b128 v[152:155], v147 offset:1024
	ds_read_b128 v[156:159], v147 offset:2048
	ds_read_b128 v[160:163], v147 offset:3072
	s_add_u32 s18, s30, 0x40000
	s_addc_u32 s19, s31, 0
	s_mov_b32 m0, s81
	v_lshl_add_u64 v[204:205], s[18:19], 0, v[130:131]
	ds_read_b128 v[168:171], v146 offset:32768
	ds_read_b128 v[176:179], v146 offset:33792
	ds_read_b128 v[180:183], v146 offset:34816
	ds_read_b128 v[184:187], v146 offset:35840
	ds_read_b128 v[188:191], v146 offset:36864
	ds_read_b128 v[192:195], v146 offset:37888
	ds_read_b128 v[196:199], v146 offset:38912
	ds_read_b128 v[200:203], v146 offset:39936
	global_load_lds_dwordx4 v[204:205], off
	v_lshl_add_u64 v[204:205], s[18:19], 0, v[132:133]
	s_mov_b32 m0, s82
	s_nop 0
	global_load_lds_dwordx4 v[204:205], off
	s_waitcnt lgkmcnt(8)
	s_barrier
; #define PG8_STAGE(bufoff, gbase, voff) do { _Pragma("unroll") for (int _i = 0; _i < 2; ++_i) \
;         __builtin_amdgcn_global_load_lds((const unsigned*)((const char*)(gbase) + (voff)[_i]), (LAS unsigned*)(lds + (bufoff) + ldsw + _i * 8192), 16, 0, 0); } while (0)
; #define PG8_LDA(dst, b, h) do { _Pragma("unroll") for (int m = 0; m < 4; ++m) _Pragma("unroll") for (int k = 0; k < 2; ++k) dst[m][k] = *(const LAS bf16x8*)(lds + PG8_SA(b, h) + aoff + m * 2048 + k * 1024); } while (0)
; #define PG8_LDB(dst, b, h) do { _Pragma("unroll") for (int n = 0; n < 2; ++n) _Pragma("unroll") for (int k = 0; k < 2; ++k) dst[n][k] = *(const LAS bf16x8*)(lds + PG8_SB(b, h) + boff + n * 2048 + k * 1024); } while (0)
; #define PG8_MMA(ai, bj, At, Bt) do { __builtin_amdgcn_s_setprio(1); _Pragma("unroll") for (int m = 0; m < 4; ++m) _Pragma("unroll") for (int n = 0; n < 2; ++n) _Pragma("unroll") for (int k = 0; k < 2; ++k) \
;         acc[ai][bj][m][n] = __builtin_amdgcn_mfma_f32_16x16x32_bf16(Bt[n][k], At[m][k], acc[ai][bj][m][n], 0, 0, 0); __builtin_amdgcn_s_setprio(0); } while (0)
; #define PG8_WAIT_V(n) asm volatile("s_waitcnt vmcnt(" #n ")" ::: "memory")
; #define PG8_WAIT_L(n) asm volatile("s_waitcnt lgkmcnt(" #n ")" ::: "memory")
; #define PG8_BAR __builtin_amdgcn_s_barrier()
; #define PG8_SCHED __builtin_amdgcn_sched_barrier(0)
; template <class Epi>
; DI void gemm_phase(int wv, LAS unsigned char* lds, const GemmD g, const Epi& E) {
;     ...
;             PG8_WAIT_V(6); PG8_BAR; PG8_MMA(1, 1, At, B1); PG8_BAR;
;             PG8_LDB(B0, 1, 0); PG8_SCHED; PG8_LDA(At, 1, 0); PG8_STAGE(PG8_SA(0, 1), a2 + hstepA, voffA);
;             PG8_WAIT_L(8); PG8_BAR; PG8_WAIT_L(0); PG8_MMA(0, 0, At, B0); PG8_BAR; PG8_SCHED;
;             PG8_LDB(B1, 1, 1); PG8_STAGE(PG8_SB(1, 0), b3, voffB);
;             PG8_BAR; PG8_WAIT_L(0); PG8_MMA(0, 1, At, B1); PG8_BAR;
;             PG8_LDA(At, 1, 1); PG8_STAGE(PG8_SA(1, 0), a3, voffA);
;             PG8_BAR; PG8_WAIT_L(0); PG8_MMA(1, 0, At, B0); PG8_BAR; PG8_SCHED;
;             PG8_STAGE(PG8_SB(1, 1), b3 + hstepB, voffB);
;             PG8_WAIT_V(6); PG8_BAR; PG8_MMA(1, 1, At, B1); PG8_BAR;
	s_waitcnt lgkmcnt(0)
	s_waitcnt lgkmcnt(0)
	v_mfma_f32_16x16x32_bf16 v[126:129], v[148:151], v[168:171], v[126:129]
	v_mfma_f32_16x16x32_bf16 v[122:125], v[156:159], v[168:171], v[122:125]
	v_mfma_f32_16x16x32_bf16 v[110:113], v[148:151], v[180:183], v[110:113]
	v_mfma_f32_16x16x32_bf16 v[106:109], v[156:159], v[180:183], v[106:109]
	v_mfma_f32_16x16x32_bf16 v[94:97], v[148:151], v[188:191], v[94:97]
	v_mfma_f32_16x16x32_bf16 v[90:93], v[156:159], v[188:191], v[90:93]
	v_mfma_f32_16x16x32_bf16 v[78:81], v[148:151], v[196:199], v[78:81]
	v_mfma_f32_16x16x32_bf16 v[74:77], v[156:159], v[196:199], v[74:77]
	v_mfma_f32_16x16x32_bf16 v[126:129], v[152:155], v[176:179], v[126:129]
	v_mfma_f32_16x16x32_bf16 v[122:125], v[160:163], v[176:179], v[122:125]
	v_mfma_f32_16x16x32_bf16 v[110:113], v[152:155], v[184:187], v[110:113]
	v_mfma_f32_16x16x32_bf16 v[106:109], v[160:163], v[184:187], v[106:109]
	v_mfma_f32_16x16x32_bf16 v[94:97], v[152:155], v[192:195], v[94:97]
	v_mfma_f32_16x16x32_bf16 v[90:93], v[160:163], v[192:195], v[90:93]
	v_mfma_f32_16x16x32_bf16 v[78:81], v[152:155], v[200:203], v[78:81]
	v_mfma_f32_16x16x32_bf16 v[74:77], v[160:163], v[200:203], v[74:77]
	s_barrier
	s_add_i32 s3, 0, 0x1c000
	s_add_i32 s2, s2, s79
	v_add_u32_e32 v147, s3, v144
	v_lshl_add_u64 v[140:141], v[140:141], 0, s[58:59]
	s_mov_b32 m0, s2
	ds_read_b128 v[204:207], v147
	ds_read_b128 v[208:211], v147 offset:1024
	ds_read_b128 v[212:215], v147 offset:2048
	ds_read_b128 v[216:219], v147 offset:3072
	global_load_lds_dwordx4 v[140:141], off
	s_add_i32 m0, s2, 0x2000
	v_lshl_add_u64 v[140:141], v[164:165], 0, s[58:59]
	global_load_lds_dwordx4 v[140:141], off
	s_barrier
	s_waitcnt lgkmcnt(0)
	s_waitcnt lgkmcnt(0)
	v_mfma_f32_16x16x32_bf16 v[118:121], v[204:207], v[168:171], v[118:121]
	v_mfma_f32_16x16x32_bf16 v[114:117], v[212:215], v[168:171], v[114:117]
	v_mfma_f32_16x16x32_bf16 v[102:105], v[204:207], v[180:183], v[102:105]
	v_mfma_f32_16x16x32_bf16 v[98:101], v[212:215], v[180:183], v[98:101]
	v_mfma_f32_16x16x32_bf16 v[86:89], v[204:207], v[188:191], v[86:89]
	v_mfma_f32_16x16x32_bf16 v[82:85], v[212:215], v[188:191], v[82:85]
	v_mfma_f32_16x16x32_bf16 v[70:73], v[204:207], v[196:199], v[70:73]
	v_mfma_f32_16x16x32_bf16 v[66:69], v[212:215], v[196:199], v[66:69]
	v_mfma_f32_16x16x32_bf16 v[118:121], v[208:211], v[176:179], v[118:121]
	v_mfma_f32_16x16x32_bf16 v[114:117], v[216:219], v[176:179], v[114:117]
	v_mfma_f32_16x16x32_bf16 v[102:105], v[208:211], v[184:187], v[102:105]
	v_mfma_f32_16x16x32_bf16 v[98:101], v[216:219], v[184:187], v[98:101]
	v_mfma_f32_16x16x32_bf16 v[86:89], v[208:211], v[192:195], v[86:89]
	v_mfma_f32_16x16x32_bf16 v[82:85], v[216:219], v[192:195], v[82:85]
	v_mfma_f32_16x16x32_bf16 v[70:73], v[208:211], v[200:203], v[70:73]
	v_mfma_f32_16x16x32_bf16 v[66:69], v[216:219], v[200:203], v[66:69]
	s_mov_b32 m0, s83
	v_lshl_add_u64 v[140:141], v[220:221], 0, s[58:59]
	s_barrier
	ds_read_b128 v[168:171], v146 offset:49152
	ds_read_b128 v[176:179], v146 offset:50176
	ds_read_b128 v[180:183], v146 offset:51200
	ds_read_b128 v[184:187], v146 offset:52224
	ds_read_b128 v[188:191], v146 offset:53248
	ds_read_b128 v[192:195], v146 offset:54272
	ds_read_b128 v[196:199], v146 offset:55296
	ds_read_b128 v[200:203], v146 offset:56320
	global_load_lds_dwordx4 v[140:141], off
	v_lshl_add_u64 v[140:141], v[222:223], 0, s[58:59]
	s_mov_b32 m0, s84
	s_nop 0
	global_load_lds_dwordx4 v[140:141], off
	s_barrier
	s_waitcnt lgkmcnt(0)
	s_waitcnt lgkmcnt(0)
	v_mfma_f32_16x16x32_bf16 v[62:65], v[148:151], v[168:171], v[62:65]
	v_mfma_f32_16x16x32_bf16 v[58:61], v[156:159], v[168:171], v[58:61]
	v_mfma_f32_16x16x32_bf16 v[46:49], v[148:151], v[180:183], v[46:49]
	v_mfma_f32_16x16x32_bf16 v[42:45], v[156:159], v[180:183], v[42:45]
	v_mfma_f32_16x16x32_bf16 v[30:33], v[148:151], v[188:191], v[30:33]
	v_mfma_f32_16x16x32_bf16 v[26:29], v[156:159], v[188:191], v[26:29]
	v_mfma_f32_16x16x32_bf16 v[14:17], v[148:151], v[196:199], v[14:17]
	v_mfma_f32_16x16x32_bf16 v[10:13], v[156:159], v[196:199], v[10:13]
	v_mfma_f32_16x16x32_bf16 v[62:65], v[152:155], v[176:179], v[62:65]
	v_mfma_f32_16x16x32_bf16 v[58:61], v[160:163], v[176:179], v[58:61]
	v_mfma_f32_16x16x32_bf16 v[46:49], v[152:155], v[184:187], v[46:49]
	v_mfma_f32_16x16x32_bf16 v[42:45], v[160:163], v[184:187], v[42:45]
	v_mfma_f32_16x16x32_bf16 v[30:33], v[152:155], v[192:195], v[30:33]
	v_mfma_f32_16x16x32_bf16 v[26:29], v[160:163], v[192:195], v[26:29]
	v_mfma_f32_16x16x32_bf16 v[14:17], v[152:155], v[200:203], v[14:17]
	v_mfma_f32_16x16x32_bf16 v[10:13], v[160:163], v[200:203], v[10:13]
	s_barrier
	s_add_u32 s18, s28, 0x40080
	s_addc_u32 s19, s29, 0
	s_add_i32 s2, s3, s79
	v_lshl_add_u64 v[140:141], s[18:19], 0, v[0:1]
	s_mov_b32 m0, s2
	s_nop 0
	global_load_lds_dwordx4 v[140:141], off
	s_add_i32 m0, s2, 0x2000
	v_lshl_add_u64 v[140:141], s[18:19], 0, v[134:135]
	global_load_lds_dwordx4 v[140:141], off
	s_waitcnt vmcnt(6)
	s_barrier
	v_mfma_f32_16x16x32_bf16 v[54:57], v[204:207], v[168:171], v[54:57]
	v_mfma_f32_16x16x32_bf16 v[50:53], v[212:215], v[168:171], v[50:53]
	v_mfma_f32_16x16x32_bf16 v[38:41], v[204:207], v[180:183], v[38:41]
	v_mfma_f32_16x16x32_bf16 v[34:37], v[212:215], v[180:183], v[34:37]
	v_mfma_f32_16x16x32_bf16 v[22:25], v[204:207], v[188:191], v[22:25]
	v_mfma_f32_16x16x32_bf16 v[18:21], v[212:215], v[188:191], v[18:21]
	v_mfma_f32_16x16x32_bf16 v[6:9], v[204:207], v[196:199], v[6:9]
	v_mfma_f32_16x16x32_bf16 v[2:5], v[212:215], v[196:199], v[2:5]
	v_mfma_f32_16x16x32_bf16 v[54:57], v[208:211], v[176:179], v[54:57]
	v_mfma_f32_16x16x32_bf16 v[50:53], v[216:219], v[176:179], v[50:53]
	v_mfma_f32_16x16x32_bf16 v[38:41], v[208:211], v[184:187], v[38:41]
	v_mfma_f32_16x16x32_bf16 v[34:37], v[216:219], v[184:187], v[34:37]
	v_mfma_f32_16x16x32_bf16 v[22:25], v[208:211], v[192:195], v[22:25]
	v_mfma_f32_16x16x32_bf16 v[18:21], v[216:219], v[192:195], v[18:21]
	v_mfma_f32_16x16x32_bf16 v[6:9], v[208:211], v[200:203], v[6:9]
	v_mfma_f32_16x16x32_bf16 v[2:5], v[216:219], v[200:203], v[2:5]
	s_add_i32 s41, s41, 2
	s_add_u32 s26, s26, 0x100
	s_addc_u32 s27, s27, 0
	s_add_u32 s36, s36, 0x100
	s_addc_u32 s38, s38, 0
	s_cmp_gt_u32 s41, 13
	s_barrier
	s_cbranch_scc0 .LBB0_490

; #define PG8_STAGE(bufoff, gbase, voff) do { _Pragma("unroll") for (int _i = 0; _i < 2; ++_i) \
;         __builtin_amdgcn_global_load_lds((const unsigned*)((const char*)(gbase) + (voff)[_i]), (LAS unsigned*)(lds + (bufoff) + ldsw + _i * 8192), 16, 0, 0); } while (0)
; #define PG8_LDA(dst, b, h) do { _Pragma("unroll") for (int m = 0; m < 4; ++m) _Pragma("unroll") for (int k = 0; k < 2; ++k) dst[m][k] = *(const LAS bf16x8*)(lds + PG8_SA(b, h) + aoff + m * 2048 + k * 1024); } while (0)
; #define PG8_LDB(dst, b, h) do { _Pragma("unroll") for (int n = 0; n < 2; ++n) _Pragma("unroll") for (int k = 0; k < 2; ++k) dst[n][k] = *(const LAS bf16x8*)(lds + PG8_SB(b, h) + boff + n * 2048 + k * 1024); } while (0)
; #define PG8_MMA(ai, bj, At, Bt) do { __builtin_amdgcn_s_setprio(1); _Pragma("unroll") for (int m = 0; m < 4; ++m) _Pragma("unroll") for (int n = 0; n < 2; ++n) _Pragma("unroll") for (int k = 0; k < 2; ++k) \
;         acc[ai][bj][m][n] = __builtin_amdgcn_mfma_f32_16x16x32_bf16(Bt[n][k], At[m][k], acc[ai][bj][m][n], 0, 0, 0); __builtin_amdgcn_s_setprio(0); } while (0)
; #define PG8_WAIT_L(n) asm volatile("s_waitcnt lgkmcnt(" #n ")" ::: "memory")
; template <class Epi>
; DI void gemm_phase(int wv, LAS unsigned char* lds, const GemmD g, const Epi& E) {
;     ...
;         const bool has_next = S.next(ui + 1, nxt);
;         const char* nA = has_next ? (const char*)g.A + (size_t)nxt.pm * 256 * g.lda * 2 : cA; const char* nB = has_next ? (const char*)g.Bt + PG8_BROW(nxt.pn) * (size_t)g.ldb * 2 : cB;
;         for (int t = 0; t < nt; t += 2) {
;             const bool last = (t == nt - 2);
;             const char* a1 = cA + (size_t)(t + 1) * kstep;
;             const char* a2 = last ? nA : cA + (size_t)(t + 2) * kstep; const char* b2 = last ? nB : cB + (size_t)(t + 2) * kstep;
;             const char* a3 = a2 + kstep; const char* b3 = b2 + kstep;
;             PG8_LDB(B0, 0, 0); PG8_SCHED; PG8_LDA(At, 0, 0); PG8_STAGE(PG8_SA(1, 1), a1 + hstepA, voffA);
;             PG8_WAIT_L(8); PG8_BAR; PG8_WAIT_L(0); PG8_MMA(0, 0, At, B0); PG8_BAR; PG8_SCHED;
;             PG8_LDB(B1, 0, 1); PG8_STAGE(PG8_SB(0, 0), b2, voffB);
;             PG8_BAR; PG8_WAIT_L(0); PG8_MMA(0, 1, At, B1); PG8_BAR;
;             PG8_LDA(At, 0, 1); PG8_STAGE(PG8_SA(0, 0), a2, voffA);
;             PG8_BAR; PG8_WAIT_L(0); PG8_MMA(1, 0, At, B0); PG8_BAR; PG8_SCHED;
.LBB0_543:
	s_ashr_i32 s23, s22, 31
	s_lshl_b64 s[18:19], s[22:23], s85
	v_cmp_lt_i64_e32 vcc, s[24:25], v[174:175]
	s_add_u32 s24, s81, s18
	s_addc_u32 s25, s80, s19
	s_and_b64 s[18:19], vcc, exec
	s_cselect_b32 s23, s25, s29
	s_cselect_b32 s68, s24, s28
	s_lshl_b32 s18, s55, 8
	s_ashr_i32 s19, s18, 31
	s_lshl_b64 s[18:19], s[18:19], s9
	s_add_u32 s26, s82, s18
	s_addc_u32 s27, s83, s19
	s_and_b64 s[18:19], vcc, exec
	s_cselect_b32 vcc_lo, s27, s31
	s_cselect_b32 vcc_hi, s26, s30
	s_add_u32 s28, s28, 0x80
	s_addc_u32 s29, s29, 0
	s_add_u32 s37, s30, 0x100
	s_addc_u32 s18, s31, 0
	s_mov_b32 s19, 0
	s_add_i32 s95, s19, 2
	s_add_u32 s2, s28, 0x80
	s_addc_u32 s3, s29, 0
	s_add_i32 s94, 0, 0x10000
	v_add_u32_e32 v145, s94, v141
	ds_read_b128 v[146:149], v145
	ds_read_b128 v[150:153], v145 offset:1024
	ds_read_b128 v[154:157], v145 offset:2048
	ds_read_b128 v[158:161], v145 offset:3072
	s_cmp_eq_u32 s17, s19
	s_cselect_b32 s31, s23, s3
	s_cselect_b32 s30, s68, s2
	s_cselect_b32 s35, vcc_lo, s18
	s_cselect_b32 s34, vcc_hi, s37
	v_lshl_add_u64 v[200:201], s[28:29], 0, v[136:137]
	s_add_i32 m0, s86, 0xc000
	ds_read_b128 v[162:165], v144
	ds_read_b128 v[168:171], v144 offset:1024
	ds_read_b128 v[176:179], v144 offset:2048
	ds_read_b128 v[180:183], v144 offset:3072
	ds_read_b128 v[184:187], v144 offset:4096
	ds_read_b128 v[188:191], v144 offset:5120
	ds_read_b128 v[192:195], v144 offset:6144
	ds_read_b128 v[196:199], v144 offset:7168
	global_load_lds_dwordx4 v[200:201], off
	s_add_i32 m0, s86, 0xe000
	v_lshl_add_u64 v[200:201], s[28:29], 0, v[138:139]
	global_load_lds_dwordx4 v[200:201], off
	s_waitcnt lgkmcnt(8)
	s_barrier
	s_waitcnt lgkmcnt(0)
	s_waitcnt lgkmcnt(0)
	v_mfma_f32_16x16x32_bf16 v[126:129], v[146:149], v[162:165], 0
	v_mfma_f32_16x16x32_bf16 v[122:125], v[154:157], v[162:165], 0
	v_mfma_f32_16x16x32_bf16 v[118:121], v[146:149], v[176:179], 0
	v_mfma_f32_16x16x32_bf16 v[114:117], v[154:157], v[176:179], 0
	v_mfma_f32_16x16x32_bf16 v[102:105], v[146:149], v[184:187], 0
	v_mfma_f32_16x16x32_bf16 v[98:101], v[154:157], v[184:187], 0
	v_mfma_f32_16x16x32_bf16 v[86:89], v[146:149], v[192:195], 0
	v_mfma_f32_16x16x32_bf16 v[82:85], v[154:157], v[192:195], 0
	v_mfma_f32_16x16x32_bf16 v[126:129], v[150:153], v[168:171], v[126:129]
	v_mfma_f32_16x16x32_bf16 v[122:125], v[158:161], v[168:171], v[122:125]
	v_mfma_f32_16x16x32_bf16 v[118:121], v[150:153], v[180:183], v[118:121]
	v_mfma_f32_16x16x32_bf16 v[114:117], v[158:161], v[180:183], v[114:117]
	v_mfma_f32_16x16x32_bf16 v[102:105], v[150:153], v[188:191], v[102:105]
	v_mfma_f32_16x16x32_bf16 v[98:101], v[158:161], v[188:191], v[98:101]
	v_mfma_f32_16x16x32_bf16 v[86:89], v[150:153], v[196:199], v[86:89]
	v_mfma_f32_16x16x32_bf16 v[82:85], v[158:161], v[196:199], v[82:85]
	s_barrier
	s_add_i32 s2, 0, 0x14000
	s_add_i32 s3, s94, s84
	v_add_u32_e32 v145, s2, v141
	v_lshl_add_u64 v[216:217], s[34:35], 0, v[0:1]
	s_mov_b32 m0, s3
	ds_read_b128 v[200:203], v145
	ds_read_b128 v[204:207], v145 offset:1024
	ds_read_b128 v[208:211], v145 offset:2048
	ds_read_b128 v[212:215], v145 offset:3072
	global_load_lds_dwordx4 v[216:217], off
	s_add_i32 m0, s3, 0x2000
	v_lshl_add_u64 v[218:219], s[34:35], 0, v[134:135]
	global_load_lds_dwordx4 v[218:219], off
	s_barrier
	s_waitcnt lgkmcnt(0)
	s_waitcnt lgkmcnt(0)
	v_mfma_f32_16x16x32_bf16 v[110:113], v[200:203], v[162:165], 0
	v_mfma_f32_16x16x32_bf16 v[106:109], v[208:211], v[162:165], 0
	v_mfma_f32_16x16x32_bf16 v[94:97], v[200:203], v[176:179], 0
	v_mfma_f32_16x16x32_bf16 v[90:93], v[208:211], v[176:179], 0
	v_mfma_f32_16x16x32_bf16 v[78:81], v[200:203], v[184:187], 0
	v_mfma_f32_16x16x32_bf16 v[74:77], v[208:211], v[184:187], 0
	v_mfma_f32_16x16x32_bf16 v[70:73], v[200:203], v[192:195], 0
	v_mfma_f32_16x16x32_bf16 v[66:69], v[208:211], v[192:195], 0
	v_mfma_f32_16x16x32_bf16 v[110:113], v[204:207], v[168:171], v[110:113]
	v_mfma_f32_16x16x32_bf16 v[106:109], v[212:215], v[168:171], v[106:109]
	v_mfma_f32_16x16x32_bf16 v[94:97], v[204:207], v[180:183], v[94:97]
	v_mfma_f32_16x16x32_bf16 v[90:93], v[212:215], v[180:183], v[90:93]
	v_mfma_f32_16x16x32_bf16 v[78:81], v[204:207], v[188:191], v[78:81]
	v_mfma_f32_16x16x32_bf16 v[74:77], v[212:215], v[188:191], v[74:77]
	v_mfma_f32_16x16x32_bf16 v[70:73], v[204:207], v[196:199], v[70:73]
	v_mfma_f32_16x16x32_bf16 v[66:69], v[212:215], v[196:199], v[66:69]
	s_mov_b32 m0, s86
	v_lshl_add_u64 v[220:221], s[30:31], 0, v[130:131]
	s_barrier
	ds_read_b128 v[162:165], v144 offset:16384
	ds_read_b128 v[168:171], v144 offset:17408
	ds_read_b128 v[176:179], v144 offset:18432
	ds_read_b128 v[180:183], v144 offset:19456
	ds_read_b128 v[184:187], v144 offset:20480
	ds_read_b128 v[188:191], v144 offset:21504
	ds_read_b128 v[192:195], v144 offset:22528
	ds_read_b128 v[196:199], v144 offset:23552
	global_load_lds_dwordx4 v[220:221], off
	v_lshl_add_u64 v[222:223], s[30:31], 0, v[132:133]
	s_mov_b32 m0, s87
	s_nop 0
	global_load_lds_dwordx4 v[222:223], off
	s_barrier
	s_waitcnt lgkmcnt(0)
	s_waitcnt lgkmcnt(0)
	v_mfma_f32_16x16x32_bf16 v[62:65], v[146:149], v[162:165], 0
	v_mfma_f32_16x16x32_bf16 v[58:61], v[154:157], v[162:165], 0
	v_mfma_f32_16x16x32_bf16 v[54:57], v[146:149], v[176:179], 0
	v_mfma_f32_16x16x32_bf16 v[50:53], v[154:157], v[176:179], 0
	v_mfma_f32_16x16x32_bf16 v[38:41], v[146:149], v[184:187], 0
	v_mfma_f32_16x16x32_bf16 v[34:37], v[154:157], v[184:187], 0
	v_mfma_f32_16x16x32_bf16 v[22:25], v[146:149], v[192:195], 0
	v_mfma_f32_16x16x32_bf16 v[18:21], v[154:157], v[192:195], 0
	v_mfma_f32_16x16x32_bf16 v[62:65], v[150:153], v[168:171], v[62:65]
	v_mfma_f32_16x16x32_bf16 v[58:61], v[158:161], v[168:171], v[58:61]
	v_mfma_f32_16x16x32_bf16 v[54:57], v[150:153], v[180:183], v[54:57]
	v_mfma_f32_16x16x32_bf16 v[50:53], v[158:161], v[180:183], v[50:53]
	v_mfma_f32_16x16x32_bf16 v[38:41], v[150:153], v[188:191], v[38:41]
	v_mfma_f32_16x16x32_bf16 v[34:37], v[158:161], v[188:191], v[34:37]
	v_mfma_f32_16x16x32_bf16 v[22:25], v[150:153], v[196:199], v[22:25]
	v_mfma_f32_16x16x32_bf16 v[18:21], v[158:161], v[196:199], v[18:21]
	s_barrier
; #define PG8_STAGE(bufoff, gbase, voff) do { _Pragma("unroll") for (int _i = 0; _i < 2; ++_i) \
;         __builtin_amdgcn_global_load_lds((const unsigned*)((const char*)(gbase) + (voff)[_i]), (LAS unsigned*)(lds + (bufoff) + ldsw + _i * 8192), 16, 0, 0); } while (0)
; #define PG8_LDA(dst, b, h) do { _Pragma("unroll") for (int m = 0; m < 4; ++m) _Pragma("unroll") for (int k = 0; k < 2; ++k) dst[m][k] = *(const LAS bf16x8*)(lds + PG8_SA(b, h) + aoff + m * 2048 + k * 1024); } while (0)
; #define PG8_LDB(dst, b, h) do { _Pragma("unroll") for (int n = 0; n < 2; ++n) _Pragma("unroll") for (int k = 0; k < 2; ++k) dst[n][k] = *(const LAS bf16x8*)(lds + PG8_SB(b, h) + boff + n * 2048 + k * 1024); } while (0)
; #define PG8_MMA(ai, bj, At, Bt) do { __builtin_amdgcn_s_setprio(1); _Pragma("unroll") for (int m = 0; m < 4; ++m) _Pragma("unroll") for (int n = 0; n < 2; ++n) _Pragma("unroll") for (int k = 0; k < 2; ++k) \
;         acc[ai][bj][m][n] = __builtin_amdgcn_mfma_f32_16x16x32_bf16(Bt[n][k], At[m][k], acc[ai][bj][m][n], 0, 0, 0); __builtin_amdgcn_s_setprio(0); } while (0)
; #define PG8_WAIT_V(n) asm volatile("s_waitcnt vmcnt(" #n ")" ::: "memory")
; #define PG8_WAIT_L(n) asm volatile("s_waitcnt lgkmcnt(" #n ")" ::: "memory")
; #define PG8_BAR __builtin_amdgcn_s_barrier()
; #define PG8_SCHED __builtin_amdgcn_sched_barrier(0)
; template <class Epi>
; DI void gemm_phase(int wv, LAS unsigned char* lds, const GemmD g, const Epi& E) {
;     ...
;             PG8_BAR; PG8_WAIT_L(0); PG8_MMA(1, 0, At, B0); PG8_BAR; PG8_SCHED;
;             PG8_STAGE(PG8_SB(0, 1), b2 + hstepB, voffB);
;             PG8_WAIT_V(6); PG8_BAR; PG8_MMA(1, 1, At, B1); PG8_BAR;
;             PG8_LDB(B0, 1, 0); PG8_SCHED; PG8_LDA(At, 1, 0); PG8_STAGE(PG8_SA(0, 1), a2 + hstepA, voffA);
;             PG8_WAIT_L(8); PG8_BAR; PG8_WAIT_L(0); PG8_MMA(0, 0, At, B0); PG8_BAR; PG8_SCHED;
;             PG8_LDB(B1, 1, 1); PG8_STAGE(PG8_SB(1, 0), b3, voffB);
;             PG8_BAR; PG8_WAIT_L(0); PG8_MMA(0, 1, At, B1); PG8_BAR;
;             PG8_LDA(At, 1, 1); PG8_STAGE(PG8_SA(1, 0), a3, voffA);
;             PG8_BAR; PG8_WAIT_L(0); PG8_MMA(1, 0, At, B0); PG8_BAR; PG8_SCHED;
	s_add_u32 s34, s34, s56
	s_addc_u32 s35, s35, 0
	s_add_i32 s2, s2, s84
	v_lshl_add_u64 v[224:225], s[34:35], 0, v[0:1]
	s_mov_b32 m0, s2
	v_lshl_add_u64 v[226:227], s[34:35], 0, v[134:135]
	global_load_lds_dwordx4 v[224:225], off
	s_add_i32 m0, s2, 0x2000
	s_nop 0
	global_load_lds_dwordx4 v[226:227], off
	s_waitcnt vmcnt(6)
	s_barrier
	v_mfma_f32_16x16x32_bf16 v[46:49], v[200:203], v[162:165], 0
	v_mfma_f32_16x16x32_bf16 v[42:45], v[208:211], v[162:165], 0
	v_mfma_f32_16x16x32_bf16 v[30:33], v[200:203], v[176:179], 0
	v_mfma_f32_16x16x32_bf16 v[26:29], v[208:211], v[176:179], 0
	v_mfma_f32_16x16x32_bf16 v[14:17], v[200:203], v[184:187], 0
	v_mfma_f32_16x16x32_bf16 v[10:13], v[208:211], v[184:187], 0
	v_mfma_f32_16x16x32_bf16 v[6:9], v[200:203], v[192:195], 0
	v_mfma_f32_16x16x32_bf16 v[2:5], v[208:211], v[192:195], 0
	v_mfma_f32_16x16x32_bf16 v[46:49], v[204:207], v[168:171], v[46:49]
	v_mfma_f32_16x16x32_bf16 v[42:45], v[212:215], v[168:171], v[42:45]
	v_mfma_f32_16x16x32_bf16 v[30:33], v[204:207], v[180:183], v[30:33]
	v_mfma_f32_16x16x32_bf16 v[26:29], v[212:215], v[180:183], v[26:29]
	v_mfma_f32_16x16x32_bf16 v[14:17], v[204:207], v[188:191], v[14:17]
	v_mfma_f32_16x16x32_bf16 v[10:13], v[212:215], v[188:191], v[10:13]
	v_mfma_f32_16x16x32_bf16 v[6:9], v[204:207], v[196:199], v[6:9]
	v_mfma_f32_16x16x32_bf16 v[2:5], v[212:215], v[196:199], v[2:5]
	s_add_i32 s2, 0, 0x18000
	v_add_u32_e32 v145, s2, v141
	s_barrier
	ds_read_b128 v[146:149], v145
	ds_read_b128 v[150:153], v145 offset:1024
	ds_read_b128 v[154:157], v145 offset:2048
	ds_read_b128 v[158:161], v145 offset:3072
	s_add_u32 s30, s30, s56
	s_addc_u32 s31, s31, 0
	s_mov_b32 m0, s74
	v_lshl_add_u64 v[200:201], s[30:31], 0, v[130:131]
	ds_read_b128 v[162:165], v144 offset:32768
	ds_read_b128 v[168:171], v144 offset:33792
	ds_read_b128 v[176:179], v144 offset:34816
	ds_read_b128 v[180:183], v144 offset:35840
	ds_read_b128 v[184:187], v144 offset:36864
	ds_read_b128 v[188:191], v144 offset:37888
	ds_read_b128 v[192:195], v144 offset:38912
	ds_read_b128 v[196:199], v144 offset:39936
	global_load_lds_dwordx4 v[200:201], off
	v_lshl_add_u64 v[200:201], s[30:31], 0, v[132:133]
	s_mov_b32 m0, s41
	s_nop 0
	global_load_lds_dwordx4 v[200:201], off
	s_waitcnt lgkmcnt(8)
	s_barrier
	s_waitcnt lgkmcnt(0)
	s_waitcnt lgkmcnt(0)
	v_mfma_f32_16x16x32_bf16 v[126:129], v[146:149], v[162:165], v[126:129]
	v_mfma_f32_16x16x32_bf16 v[122:125], v[154:157], v[162:165], v[122:125]
	v_mfma_f32_16x16x32_bf16 v[118:121], v[146:149], v[176:179], v[118:121]
	v_mfma_f32_16x16x32_bf16 v[114:117], v[154:157], v[176:179], v[114:117]
	v_mfma_f32_16x16x32_bf16 v[102:105], v[146:149], v[184:187], v[102:105]
	v_mfma_f32_16x16x32_bf16 v[98:101], v[154:157], v[184:187], v[98:101]
	v_mfma_f32_16x16x32_bf16 v[86:89], v[146:149], v[192:195], v[86:89]
	v_mfma_f32_16x16x32_bf16 v[82:85], v[154:157], v[192:195], v[82:85]
	v_mfma_f32_16x16x32_bf16 v[126:129], v[150:153], v[168:171], v[126:129]
	v_mfma_f32_16x16x32_bf16 v[122:125], v[158:161], v[168:171], v[122:125]
	v_mfma_f32_16x16x32_bf16 v[118:121], v[150:153], v[180:183], v[118:121]
	v_mfma_f32_16x16x32_bf16 v[114:117], v[158:161], v[180:183], v[114:117]
	v_mfma_f32_16x16x32_bf16 v[102:105], v[150:153], v[188:191], v[102:105]
	v_mfma_f32_16x16x32_bf16 v[98:101], v[158:161], v[188:191], v[98:101]
	v_mfma_f32_16x16x32_bf16 v[86:89], v[150:153], v[196:199], v[86:89]
	v_mfma_f32_16x16x32_bf16 v[82:85], v[158:161], v[196:199], v[82:85]
	s_barrier
	s_add_i32 s3, 0, 0x1c000
	s_add_i32 s2, s2, s84
	v_add_u32_e32 v145, s3, v141
	v_lshl_add_u64 v[216:217], v[216:217], 0, s[58:59]
	s_mov_b32 m0, s2
	ds_read_b128 v[200:203], v145
	ds_read_b128 v[204:207], v145 offset:1024
	ds_read_b128 v[208:211], v145 offset:2048
	ds_read_b128 v[212:215], v145 offset:3072
	global_load_lds_dwordx4 v[216:217], off
	s_add_i32 m0, s2, 0x2000
	v_lshl_add_u64 v[216:217], v[218:219], 0, s[58:59]
	global_load_lds_dwordx4 v[216:217], off
	s_barrier
	s_waitcnt lgkmcnt(0)
	s_waitcnt lgkmcnt(0)
	v_mfma_f32_16x16x32_bf16 v[110:113], v[200:203], v[162:165], v[110:113]
	v_mfma_f32_16x16x32_bf16 v[106:109], v[208:211], v[162:165], v[106:109]
	v_mfma_f32_16x16x32_bf16 v[94:97], v[200:203], v[176:179], v[94:97]
	v_mfma_f32_16x16x32_bf16 v[90:93], v[208:211], v[176:179], v[90:93]
	v_mfma_f32_16x16x32_bf16 v[78:81], v[200:203], v[184:187], v[78:81]
	v_mfma_f32_16x16x32_bf16 v[74:77], v[208:211], v[184:187], v[74:77]
	v_mfma_f32_16x16x32_bf16 v[70:73], v[200:203], v[192:195], v[70:73]
	v_mfma_f32_16x16x32_bf16 v[66:69], v[208:211], v[192:195], v[66:69]
	v_mfma_f32_16x16x32_bf16 v[110:113], v[204:207], v[168:171], v[110:113]
	v_mfma_f32_16x16x32_bf16 v[106:109], v[212:215], v[168:171], v[106:109]
	v_mfma_f32_16x16x32_bf16 v[94:97], v[204:207], v[180:183], v[94:97]
	v_mfma_f32_16x16x32_bf16 v[90:93], v[212:215], v[180:183], v[90:93]
	v_mfma_f32_16x16x32_bf16 v[78:81], v[204:207], v[188:191], v[78:81]
	v_mfma_f32_16x16x32_bf16 v[74:77], v[212:215], v[188:191], v[74:77]
	v_mfma_f32_16x16x32_bf16 v[70:73], v[204:207], v[196:199], v[70:73]
	v_mfma_f32_16x16x32_bf16 v[66:69], v[212:215], v[196:199], v[66:69]
	s_mov_b32 m0, s13
	v_lshl_add_u64 v[216:217], v[220:221], 0, s[58:59]
	s_barrier
	ds_read_b128 v[162:165], v144 offset:49152
	ds_read_b128 v[168:171], v144 offset:50176
	ds_read_b128 v[176:179], v144 offset:51200
	ds_read_b128 v[180:183], v144 offset:52224
	ds_read_b128 v[184:187], v144 offset:53248
	ds_read_b128 v[188:191], v144 offset:54272
	ds_read_b128 v[192:195], v144 offset:55296
	ds_read_b128 v[196:199], v144 offset:56320
	global_load_lds_dwordx4 v[216:217], off
	v_lshl_add_u64 v[216:217], v[222:223], 0, s[58:59]
	s_mov_b32 m0, s16
	s_nop 0
	global_load_lds_dwordx4 v[216:217], off
	s_barrier
; #define PG8_STAGE(bufoff, gbase, voff) do { _Pragma("unroll") for (int _i = 0; _i < 2; ++_i) \
;         __builtin_amdgcn_global_load_lds((const unsigned*)((const char*)(gbase) + (voff)[_i]), (LAS unsigned*)(lds + (bufoff) + ldsw + _i * 8192), 16, 0, 0); } while (0)
; #define PG8_LDA(dst, b, h) do { _Pragma("unroll") for (int m = 0; m < 4; ++m) _Pragma("unroll") for (int k = 0; k < 2; ++k) dst[m][k] = *(const LAS bf16x8*)(lds + PG8_SA(b, h) + aoff + m * 2048 + k * 1024); } while (0)
; #define PG8_LDB(dst, b, h) do { _Pragma("unroll") for (int n = 0; n < 2; ++n) _Pragma("unroll") for (int k = 0; k < 2; ++k) dst[n][k] = *(const LAS bf16x8*)(lds + PG8_SB(b, h) + boff + n * 2048 + k * 1024); } while (0)
; #define PG8_WAIT_V(n) asm volatile("s_waitcnt vmcnt(" #n ")" ::: "memory")
; #define PG8_WAIT_L(n) asm volatile("s_waitcnt lgkmcnt(" #n ")" ::: "memory")
; #define PG8_BAR __builtin_amdgcn_s_barrier()
; #define PG8_SCHED __builtin_amdgcn_sched_barrier(0)
; template <class Epi>
; DI void gemm_phase(int wv, LAS unsigned char* lds, const GemmD g, const Epi& E) {
;     ...
;             PG8_LDB(B0, 0, 0); PG8_SCHED; PG8_LDA(At, 0, 0); PG8_STAGE(PG8_SA(1, 1), a1 + hstepA, voffA);
;             PG8_WAIT_L(8); PG8_BAR; PG8_WAIT_L(0); PG8_MMA(0, 0, At, B0); PG8_BAR; PG8_SCHED;
;             PG8_LDB(B1, 0, 1); PG8_STAGE(PG8_SB(0, 0), b2, voffB);
;             PG8_BAR; PG8_WAIT_L(0); PG8_MMA(0, 1, At, B1); PG8_BAR;
;             PG8_LDA(At, 0, 1); PG8_STAGE(PG8_SA(0, 0), a2, voffA);
;             PG8_BAR; PG8_WAIT_L(0); PG8_MMA(1, 0, At, B0); PG8_BAR; PG8_SCHED;
;             PG8_STAGE(PG8_SB(0, 1), b2 + hstepB, voffB);
;             PG8_WAIT_V(6); PG8_BAR; PG8_MMA(1, 1, At, B1); PG8_BAR;
;             PG8_LDB(B0, 1, 0); PG8_SCHED; PG8_LDA(At, 1, 0); PG8_STAGE(PG8_SA(0, 1), a2 + hstepA, voffA);
;             PG8_WAIT_L(8); PG8_BAR; PG8_WAIT_L(0); PG8_MMA(0, 0, At, B0); PG8_BAR; PG8_SCHED;
;             PG8_LDB(B1, 1, 1); PG8_STAGE(PG8_SB(1, 0), b3, voffB);
;             PG8_BAR; PG8_WAIT_L(0); PG8_MMA(0, 1, At, B1); PG8_BAR;
;             PG8_LDA(At, 1, 1); PG8_STAGE(PG8_SA(1, 0), a3, voffA);
;             PG8_BAR; PG8_WAIT_L(0); PG8_MMA(1, 0, At, B0); PG8_BAR; PG8_SCHED;
;             PG8_STAGE(PG8_SB(1, 1), b3 + hstepB, voffB);
;             PG8_WAIT_V(6); PG8_BAR; PG8_MMA(1, 1, At, B1); PG8_BAR;
	s_waitcnt lgkmcnt(0)
	s_waitcnt lgkmcnt(0)
	v_mfma_f32_16x16x32_bf16 v[62:65], v[146:149], v[162:165], v[62:65]
	v_mfma_f32_16x16x32_bf16 v[58:61], v[154:157], v[162:165], v[58:61]
	v_mfma_f32_16x16x32_bf16 v[54:57], v[146:149], v[176:179], v[54:57]
	v_mfma_f32_16x16x32_bf16 v[50:53], v[154:157], v[176:179], v[50:53]
	v_mfma_f32_16x16x32_bf16 v[38:41], v[146:149], v[184:187], v[38:41]
	v_mfma_f32_16x16x32_bf16 v[34:37], v[154:157], v[184:187], v[34:37]
	v_mfma_f32_16x16x32_bf16 v[22:25], v[146:149], v[192:195], v[22:25]
	v_mfma_f32_16x16x32_bf16 v[18:21], v[154:157], v[192:195], v[18:21]
	v_mfma_f32_16x16x32_bf16 v[62:65], v[150:153], v[168:171], v[62:65]
	v_mfma_f32_16x16x32_bf16 v[58:61], v[158:161], v[168:171], v[58:61]
	v_mfma_f32_16x16x32_bf16 v[54:57], v[150:153], v[180:183], v[54:57]
	v_mfma_f32_16x16x32_bf16 v[50:53], v[158:161], v[180:183], v[50:53]
	v_mfma_f32_16x16x32_bf16 v[38:41], v[150:153], v[188:191], v[38:41]
	v_mfma_f32_16x16x32_bf16 v[34:37], v[158:161], v[188:191], v[34:37]
	v_mfma_f32_16x16x32_bf16 v[22:25], v[150:153], v[196:199], v[22:25]
	v_mfma_f32_16x16x32_bf16 v[18:21], v[158:161], v[196:199], v[18:21]
	s_barrier
	s_add_i32 s2, s3, s84
	v_lshl_add_u64 v[146:147], v[224:225], 0, s[58:59]
	s_mov_b32 m0, s2
	s_nop 0
	global_load_lds_dwordx4 v[146:147], off
	s_add_i32 m0, s2, 0x2000
	v_lshl_add_u64 v[146:147], v[226:227], 0, s[58:59]
	global_load_lds_dwordx4 v[146:147], off
	s_waitcnt vmcnt(6)
	s_barrier
	v_mfma_f32_16x16x32_bf16 v[46:49], v[200:203], v[162:165], v[46:49]
	v_mfma_f32_16x16x32_bf16 v[42:45], v[208:211], v[162:165], v[42:45]
	v_mfma_f32_16x16x32_bf16 v[30:33], v[200:203], v[176:179], v[30:33]
	v_mfma_f32_16x16x32_bf16 v[26:29], v[208:211], v[176:179], v[26:29]
	v_mfma_f32_16x16x32_bf16 v[14:17], v[200:203], v[184:187], v[14:17]
	v_mfma_f32_16x16x32_bf16 v[10:13], v[208:211], v[184:187], v[10:13]
	v_mfma_f32_16x16x32_bf16 v[6:9], v[200:203], v[192:195], v[6:9]
	v_mfma_f32_16x16x32_bf16 v[2:5], v[208:211], v[192:195], v[2:5]
	v_mfma_f32_16x16x32_bf16 v[46:49], v[204:207], v[168:171], v[46:49]
	v_mfma_f32_16x16x32_bf16 v[42:45], v[212:215], v[168:171], v[42:45]
	v_mfma_f32_16x16x32_bf16 v[30:33], v[204:207], v[180:183], v[30:33]
	v_mfma_f32_16x16x32_bf16 v[26:29], v[212:215], v[180:183], v[26:29]
	v_mfma_f32_16x16x32_bf16 v[14:17], v[204:207], v[188:191], v[14:17]
	v_mfma_f32_16x16x32_bf16 v[10:13], v[212:215], v[188:191], v[10:13]
	v_mfma_f32_16x16x32_bf16 v[6:9], v[204:207], v[196:199], v[6:9]
	v_mfma_f32_16x16x32_bf16 v[2:5], v[212:215], v[196:199], v[2:5]
	s_add_u32 s28, s28, 0x100
	s_addc_u32 s29, s29, 0
	s_add_u32 s37, s37, 0x100
	s_addc_u32 s18, s18, 0
	s_cmp_ge_u32 s95, s38
	s_mov_b32 s19, s95
	s_barrier
	s_cbranch_scc0 .LBB0_544
	s_branch .Lgemm_epi_c
	.p2align 6
.LBB0_544:
	s_add_i32 s95, s19, 2
	s_add_u32 s2, s28, 0x80
	s_addc_u32 s3, s29, 0
	s_add_i32 s94, 0, 0x10000
	v_add_u32_e32 v145, s94, v141
	ds_read_b128 v[146:149], v145
	ds_read_b128 v[150:153], v145 offset:1024
	ds_read_b128 v[154:157], v145 offset:2048
	ds_read_b128 v[158:161], v145 offset:3072
	s_cmp_eq_u32 s17, s19
	s_cselect_b32 s31, s23, s3
	s_cselect_b32 s30, s68, s2
	s_cselect_b32 s35, vcc_lo, s18
	s_cselect_b32 s34, vcc_hi, s37
	v_lshl_add_u64 v[200:201], s[28:29], 0, v[136:137]
	s_add_i32 m0, s86, 0xc000
	ds_read_b128 v[162:165], v144
	ds_read_b128 v[168:171], v144 offset:1024
	ds_read_b128 v[176:179], v144 offset:2048
	ds_read_b128 v[180:183], v144 offset:3072
	ds_read_b128 v[184:187], v144 offset:4096
	ds_read_b128 v[188:191], v144 offset:5120
	ds_read_b128 v[192:195], v144 offset:6144
	ds_read_b128 v[196:199], v144 offset:7168
	global_load_lds_dwordx4 v[200:201], off
	s_add_i32 m0, s86, 0xe000
	v_lshl_add_u64 v[200:201], s[28:29], 0, v[138:139]
	global_load_lds_dwordx4 v[200:201], off
	s_waitcnt lgkmcnt(8)
	s_barrier
	s_waitcnt lgkmcnt(0)
	s_waitcnt lgkmcnt(0)
	v_mfma_f32_16x16x32_bf16 v[126:129], v[146:149], v[162:165], v[126:129]
	v_mfma_f32_16x16x32_bf16 v[122:125], v[154:157], v[162:165], v[122:125]
	v_mfma_f32_16x16x32_bf16 v[118:121], v[146:149], v[176:179], v[118:121]
	v_mfma_f32_16x16x32_bf16 v[114:117], v[154:157], v[176:179], v[114:117]
	v_mfma_f32_16x16x32_bf16 v[102:105], v[146:149], v[184:187], v[102:105]
	v_mfma_f32_16x16x32_bf16 v[98:101], v[154:157], v[184:187], v[98:101]
	v_mfma_f32_16x16x32_bf16 v[86:89], v[146:149], v[192:195], v[86:89]
	v_mfma_f32_16x16x32_bf16 v[82:85], v[154:157], v[192:195], v[82:85]
	v_mfma_f32_16x16x32_bf16 v[126:129], v[150:153], v[168:171], v[126:129]
	v_mfma_f32_16x16x32_bf16 v[122:125], v[158:161], v[168:171], v[122:125]
	v_mfma_f32_16x16x32_bf16 v[118:121], v[150:153], v[180:183], v[118:121]
	v_mfma_f32_16x16x32_bf16 v[114:117], v[158:161], v[180:183], v[114:117]
	v_mfma_f32_16x16x32_bf16 v[102:105], v[150:153], v[188:191], v[102:105]
	v_mfma_f32_16x16x32_bf16 v[98:101], v[158:161], v[188:191], v[98:101]
	v_mfma_f32_16x16x32_bf16 v[86:89], v[150:153], v[196:199], v[86:89]
	v_mfma_f32_16x16x32_bf16 v[82:85], v[158:161], v[196:199], v[82:85]
	s_barrier
	s_add_i32 s2, 0, 0x14000
	s_add_i32 s3, s94, s84
	v_add_u32_e32 v145, s2, v141
	v_lshl_add_u64 v[216:217], s[34:35], 0, v[0:1]
	s_mov_b32 m0, s3
	ds_read_b128 v[200:203], v145
	ds_read_b128 v[204:207], v145 offset:1024
	ds_read_b128 v[208:211], v145 offset:2048
	ds_read_b128 v[212:215], v145 offset:3072
	global_load_lds_dwordx4 v[216:217], off
	s_add_i32 m0, s3, 0x2000
	v_lshl_add_u64 v[218:219], s[34:35], 0, v[134:135]
	global_load_lds_dwordx4 v[218:219], off
	s_barrier
; #define PG8_STAGE(bufoff, gbase, voff) do { _Pragma("unroll") for (int _i = 0; _i < 2; ++_i) \
;         __builtin_amdgcn_global_load_lds((const unsigned*)((const char*)(gbase) + (voff)[_i]), (LAS unsigned*)(lds + (bufoff) + ldsw + _i * 8192), 16, 0, 0); } while (0)
; #define PG8_LDA(dst, b, h) do { _Pragma("unroll") for (int m = 0; m < 4; ++m) _Pragma("unroll") for (int k = 0; k < 2; ++k) dst[m][k] = *(const LAS bf16x8*)(lds + PG8_SA(b, h) + aoff + m * 2048 + k * 1024); } while (0)
; #define PG8_LDB(dst, b, h) do { _Pragma("unroll") for (int n = 0; n < 2; ++n) _Pragma("unroll") for (int k = 0; k < 2; ++k) dst[n][k] = *(const LAS bf16x8*)(lds + PG8_SB(b, h) + boff + n * 2048 + k * 1024); } while (0)
; #define PG8_MMA(ai, bj, At, Bt) do { __builtin_amdgcn_s_setprio(1); _Pragma("unroll") for (int m = 0; m < 4; ++m) _Pragma("unroll") for (int n = 0; n < 2; ++n) _Pragma("unroll") for (int k = 0; k < 2; ++k) \
;         acc[ai][bj][m][n] = __builtin_amdgcn_mfma_f32_16x16x32_bf16(Bt[n][k], At[m][k], acc[ai][bj][m][n], 0, 0, 0); __builtin_amdgcn_s_setprio(0); } while (0)
; #define PG8_WAIT_V(n) asm volatile("s_waitcnt vmcnt(" #n ")" ::: "memory")
; #define PG8_WAIT_L(n) asm volatile("s_waitcnt lgkmcnt(" #n ")" ::: "memory")
; #define PG8_BAR __builtin_amdgcn_s_barrier()
; #define PG8_SCHED __builtin_amdgcn_sched_barrier(0)
; template <class Epi>
; DI void gemm_phase(int wv, LAS unsigned char* lds, const GemmD g, const Epi& E) {
;     ...
;             PG8_BAR; PG8_WAIT_L(0); PG8_MMA(0, 1, At, B1); PG8_BAR;
;             PG8_LDA(At, 0, 1); PG8_STAGE(PG8_SA(0, 0), a2, voffA);
;             PG8_BAR; PG8_WAIT_L(0); PG8_MMA(1, 0, At, B0); PG8_BAR; PG8_SCHED;
;             PG8_STAGE(PG8_SB(0, 1), b2 + hstepB, voffB);
;             PG8_WAIT_V(6); PG8_BAR; PG8_MMA(1, 1, At, B1); PG8_BAR;
;             PG8_LDB(B0, 1, 0); PG8_SCHED; PG8_LDA(At, 1, 0); PG8_STAGE(PG8_SA(0, 1), a2 + hstepA, voffA);
;             PG8_WAIT_L(8); PG8_BAR; PG8_WAIT_L(0); PG8_MMA(0, 0, At, B0); PG8_BAR; PG8_SCHED;
	s_waitcnt lgkmcnt(0)
	s_waitcnt lgkmcnt(0)
	v_mfma_f32_16x16x32_bf16 v[110:113], v[200:203], v[162:165], v[110:113]
	v_mfma_f32_16x16x32_bf16 v[106:109], v[208:211], v[162:165], v[106:109]
	v_mfma_f32_16x16x32_bf16 v[94:97], v[200:203], v[176:179], v[94:97]
	v_mfma_f32_16x16x32_bf16 v[90:93], v[208:211], v[176:179], v[90:93]
	v_mfma_f32_16x16x32_bf16 v[78:81], v[200:203], v[184:187], v[78:81]
	v_mfma_f32_16x16x32_bf16 v[74:77], v[208:211], v[184:187], v[74:77]
	v_mfma_f32_16x16x32_bf16 v[70:73], v[200:203], v[192:195], v[70:73]
	v_mfma_f32_16x16x32_bf16 v[66:69], v[208:211], v[192:195], v[66:69]
	v_mfma_f32_16x16x32_bf16 v[110:113], v[204:207], v[168:171], v[110:113]
	v_mfma_f32_16x16x32_bf16 v[106:109], v[212:215], v[168:171], v[106:109]
	v_mfma_f32_16x16x32_bf16 v[94:97], v[204:207], v[180:183], v[94:97]
	v_mfma_f32_16x16x32_bf16 v[90:93], v[212:215], v[180:183], v[90:93]
	v_mfma_f32_16x16x32_bf16 v[78:81], v[204:207], v[188:191], v[78:81]
	v_mfma_f32_16x16x32_bf16 v[74:77], v[212:215], v[188:191], v[74:77]
	v_mfma_f32_16x16x32_bf16 v[70:73], v[204:207], v[196:199], v[70:73]
	v_mfma_f32_16x16x32_bf16 v[66:69], v[212:215], v[196:199], v[66:69]
	s_mov_b32 m0, s86
	v_lshl_add_u64 v[220:221], s[30:31], 0, v[130:131]
	s_barrier
	ds_read_b128 v[162:165], v144 offset:16384
	ds_read_b128 v[168:171], v144 offset:17408
	ds_read_b128 v[176:179], v144 offset:18432
	ds_read_b128 v[180:183], v144 offset:19456
	ds_read_b128 v[184:187], v144 offset:20480
	ds_read_b128 v[188:191], v144 offset:21504
	ds_read_b128 v[192:195], v144 offset:22528
	ds_read_b128 v[196:199], v144 offset:23552
	global_load_lds_dwordx4 v[220:221], off
	v_lshl_add_u64 v[222:223], s[30:31], 0, v[132:133]
	s_mov_b32 m0, s87
	s_nop 0
	global_load_lds_dwordx4 v[222:223], off
	s_barrier
	s_waitcnt lgkmcnt(0)
	s_waitcnt lgkmcnt(0)
	v_mfma_f32_16x16x32_bf16 v[62:65], v[146:149], v[162:165], v[62:65]
	v_mfma_f32_16x16x32_bf16 v[58:61], v[154:157], v[162:165], v[58:61]
	v_mfma_f32_16x16x32_bf16 v[54:57], v[146:149], v[176:179], v[54:57]
	v_mfma_f32_16x16x32_bf16 v[50:53], v[154:157], v[176:179], v[50:53]
	v_mfma_f32_16x16x32_bf16 v[38:41], v[146:149], v[184:187], v[38:41]
	v_mfma_f32_16x16x32_bf16 v[34:37], v[154:157], v[184:187], v[34:37]
	v_mfma_f32_16x16x32_bf16 v[22:25], v[146:149], v[192:195], v[22:25]
	v_mfma_f32_16x16x32_bf16 v[18:21], v[154:157], v[192:195], v[18:21]
	v_mfma_f32_16x16x32_bf16 v[62:65], v[150:153], v[168:171], v[62:65]
	v_mfma_f32_16x16x32_bf16 v[58:61], v[158:161], v[168:171], v[58:61]
	v_mfma_f32_16x16x32_bf16 v[54:57], v[150:153], v[180:183], v[54:57]
	v_mfma_f32_16x16x32_bf16 v[50:53], v[158:161], v[180:183], v[50:53]
	v_mfma_f32_16x16x32_bf16 v[38:41], v[150:153], v[188:191], v[38:41]
	v_mfma_f32_16x16x32_bf16 v[34:37], v[158:161], v[188:191], v[34:37]
	v_mfma_f32_16x16x32_bf16 v[22:25], v[150:153], v[196:199], v[22:25]
	v_mfma_f32_16x16x32_bf16 v[18:21], v[158:161], v[196:199], v[18:21]
	s_barrier
	s_add_u32 s34, s34, s56
	s_addc_u32 s35, s35, 0
	s_add_i32 s2, s2, s84
	v_lshl_add_u64 v[224:225], s[34:35], 0, v[0:1]
	s_mov_b32 m0, s2
	v_lshl_add_u64 v[226:227], s[34:35], 0, v[134:135]
	global_load_lds_dwordx4 v[224:225], off
	s_add_i32 m0, s2, 0x2000
	s_nop 0
	global_load_lds_dwordx4 v[226:227], off
	s_waitcnt vmcnt(6)
	s_barrier
	v_mfma_f32_16x16x32_bf16 v[46:49], v[200:203], v[162:165], v[46:49]
	v_mfma_f32_16x16x32_bf16 v[42:45], v[208:211], v[162:165], v[42:45]
	v_mfma_f32_16x16x32_bf16 v[30:33], v[200:203], v[176:179], v[30:33]
	v_mfma_f32_16x16x32_bf16 v[26:29], v[208:211], v[176:179], v[26:29]
	v_mfma_f32_16x16x32_bf16 v[14:17], v[200:203], v[184:187], v[14:17]
	v_mfma_f32_16x16x32_bf16 v[10:13], v[208:211], v[184:187], v[10:13]
	v_mfma_f32_16x16x32_bf16 v[6:9], v[200:203], v[192:195], v[6:9]
	v_mfma_f32_16x16x32_bf16 v[2:5], v[208:211], v[192:195], v[2:5]
	v_mfma_f32_16x16x32_bf16 v[46:49], v[204:207], v[168:171], v[46:49]
	v_mfma_f32_16x16x32_bf16 v[42:45], v[212:215], v[168:171], v[42:45]
	v_mfma_f32_16x16x32_bf16 v[30:33], v[204:207], v[180:183], v[30:33]
	v_mfma_f32_16x16x32_bf16 v[26:29], v[212:215], v[180:183], v[26:29]
	v_mfma_f32_16x16x32_bf16 v[14:17], v[204:207], v[188:191], v[14:17]
	v_mfma_f32_16x16x32_bf16 v[10:13], v[212:215], v[188:191], v[10:13]
	v_mfma_f32_16x16x32_bf16 v[6:9], v[204:207], v[196:199], v[6:9]
	v_mfma_f32_16x16x32_bf16 v[2:5], v[212:215], v[196:199], v[2:5]
	s_add_i32 s2, 0, 0x18000
	v_add_u32_e32 v145, s2, v141
	s_barrier
	ds_read_b128 v[146:149], v145
	ds_read_b128 v[150:153], v145 offset:1024
	ds_read_b128 v[154:157], v145 offset:2048
	ds_read_b128 v[158:161], v145 offset:3072
	s_add_u32 s30, s30, s56
	s_addc_u32 s31, s31, 0
	s_mov_b32 m0, s74
	v_lshl_add_u64 v[200:201], s[30:31], 0, v[130:131]
	ds_read_b128 v[162:165], v144 offset:32768
	ds_read_b128 v[168:171], v144 offset:33792
	ds_read_b128 v[176:179], v144 offset:34816
	ds_read_b128 v[180:183], v144 offset:35840
	ds_read_b128 v[184:187], v144 offset:36864
	ds_read_b128 v[188:191], v144 offset:37888
	ds_read_b128 v[192:195], v144 offset:38912
	ds_read_b128 v[196:199], v144 offset:39936
	global_load_lds_dwordx4 v[200:201], off
	v_lshl_add_u64 v[200:201], s[30:31], 0, v[132:133]
	s_mov_b32 m0, s41
	s_nop 0
	global_load_lds_dwordx4 v[200:201], off
	s_waitcnt lgkmcnt(8)
	s_barrier
; #define PG8_STAGE(bufoff, gbase, voff) do { _Pragma("unroll") for (int _i = 0; _i < 2; ++_i) \
;         __builtin_amdgcn_global_load_lds((const unsigned*)((const char*)(gbase) + (voff)[_i]), (LAS unsigned*)(lds + (bufoff) + ldsw + _i * 8192), 16, 0, 0); } while (0)
; #define PG8_LDA(dst, b, h) do { _Pragma("unroll") for (int m = 0; m < 4; ++m) _Pragma("unroll") for (int k = 0; k < 2; ++k) dst[m][k] = *(const LAS bf16x8*)(lds + PG8_SA(b, h) + aoff + m * 2048 + k * 1024); } while (0)
; #define PG8_LDB(dst, b, h) do { _Pragma("unroll") for (int n = 0; n < 2; ++n) _Pragma("unroll") for (int k = 0; k < 2; ++k) dst[n][k] = *(const LAS bf16x8*)(lds + PG8_SB(b, h) + boff + n * 2048 + k * 1024); } while (0)
; #define PG8_MMA(ai, bj, At, Bt) do { __builtin_amdgcn_s_setprio(1); _Pragma("unroll") for (int m = 0; m < 4; ++m) _Pragma("unroll") for (int n = 0; n < 2; ++n) _Pragma("unroll") for (int k = 0; k < 2; ++k) \
;         acc[ai][bj][m][n] = __builtin_amdgcn_mfma_f32_16x16x32_bf16(Bt[n][k], At[m][k], acc[ai][bj][m][n], 0, 0, 0); __builtin_amdgcn_s_setprio(0); } while (0)
; #define PG8_WAIT_V(n) asm volatile("s_waitcnt vmcnt(" #n ")" ::: "memory")
; #define PG8_WAIT_L(n) asm volatile("s_waitcnt lgkmcnt(" #n ")" ::: "memory")
; #define PG8_BAR __builtin_amdgcn_s_barrier()
; #define PG8_SCHED __builtin_amdgcn_sched_barrier(0)
; template <class Epi>
; DI void gemm_phase(int wv, LAS unsigned char* lds, const GemmD g, const Epi& E) {
;     ...
;             PG8_WAIT_L(8); PG8_BAR; PG8_WAIT_L(0); PG8_MMA(0, 0, At, B0); PG8_BAR; PG8_SCHED;
;             PG8_LDB(B1, 1, 1); PG8_STAGE(PG8_SB(1, 0), b3, voffB);
;             PG8_BAR; PG8_WAIT_L(0); PG8_MMA(0, 1, At, B1); PG8_BAR;
;             PG8_LDA(At, 1, 1); PG8_STAGE(PG8_SA(1, 0), a3, voffA);
;             PG8_BAR; PG8_WAIT_L(0); PG8_MMA(1, 0, At, B0); PG8_BAR; PG8_SCHED;
;             PG8_STAGE(PG8_SB(1, 1), b3 + hstepB, voffB);
;             PG8_WAIT_V(6); PG8_BAR; PG8_MMA(1, 1, At, B1); PG8_BAR;
	s_waitcnt lgkmcnt(0)
	s_waitcnt lgkmcnt(0)
	v_mfma_f32_16x16x32_bf16 v[126:129], v[146:149], v[162:165], v[126:129]
	v_mfma_f32_16x16x32_bf16 v[122:125], v[154:157], v[162:165], v[122:125]
	v_mfma_f32_16x16x32_bf16 v[118:121], v[146:149], v[176:179], v[118:121]
	v_mfma_f32_16x16x32_bf16 v[114:117], v[154:157], v[176:179], v[114:117]
	v_mfma_f32_16x16x32_bf16 v[102:105], v[146:149], v[184:187], v[102:105]
	v_mfma_f32_16x16x32_bf16 v[98:101], v[154:157], v[184:187], v[98:101]
	v_mfma_f32_16x16x32_bf16 v[86:89], v[146:149], v[192:195], v[86:89]
	v_mfma_f32_16x16x32_bf16 v[82:85], v[154:157], v[192:195], v[82:85]
	v_mfma_f32_16x16x32_bf16 v[126:129], v[150:153], v[168:171], v[126:129]
	v_mfma_f32_16x16x32_bf16 v[122:125], v[158:161], v[168:171], v[122:125]
	v_mfma_f32_16x16x32_bf16 v[118:121], v[150:153], v[180:183], v[118:121]
	v_mfma_f32_16x16x32_bf16 v[114:117], v[158:161], v[180:183], v[114:117]
	v_mfma_f32_16x16x32_bf16 v[102:105], v[150:153], v[188:191], v[102:105]
	v_mfma_f32_16x16x32_bf16 v[98:101], v[158:161], v[188:191], v[98:101]
	v_mfma_f32_16x16x32_bf16 v[86:89], v[150:153], v[196:199], v[86:89]
	v_mfma_f32_16x16x32_bf16 v[82:85], v[158:161], v[196:199], v[82:85]
	s_barrier
	s_add_i32 s3, 0, 0x1c000
	s_add_i32 s2, s2, s84
	v_add_u32_e32 v145, s3, v141
	v_lshl_add_u64 v[216:217], v[216:217], 0, s[58:59]
	s_mov_b32 m0, s2
	ds_read_b128 v[200:203], v145
	ds_read_b128 v[204:207], v145 offset:1024
	ds_read_b128 v[208:211], v145 offset:2048
	ds_read_b128 v[212:215], v145 offset:3072
	global_load_lds_dwordx4 v[216:217], off
	s_add_i32 m0, s2, 0x2000
	v_lshl_add_u64 v[216:217], v[218:219], 0, s[58:59]
	global_load_lds_dwordx4 v[216:217], off
	s_barrier
	s_waitcnt lgkmcnt(0)
	s_waitcnt lgkmcnt(0)
	v_mfma_f32_16x16x32_bf16 v[110:113], v[200:203], v[162:165], v[110:113]
	v_mfma_f32_16x16x32_bf16 v[106:109], v[208:211], v[162:165], v[106:109]
	v_mfma_f32_16x16x32_bf16 v[94:97], v[200:203], v[176:179], v[94:97]
	v_mfma_f32_16x16x32_bf16 v[90:93], v[208:211], v[176:179], v[90:93]
	v_mfma_f32_16x16x32_bf16 v[78:81], v[200:203], v[184:187], v[78:81]
	v_mfma_f32_16x16x32_bf16 v[74:77], v[208:211], v[184:187], v[74:77]
	v_mfma_f32_16x16x32_bf16 v[70:73], v[200:203], v[192:195], v[70:73]
	v_mfma_f32_16x16x32_bf16 v[66:69], v[208:211], v[192:195], v[66:69]
	v_mfma_f32_16x16x32_bf16 v[110:113], v[204:207], v[168:171], v[110:113]
	v_mfma_f32_16x16x32_bf16 v[106:109], v[212:215], v[168:171], v[106:109]
	v_mfma_f32_16x16x32_bf16 v[94:97], v[204:207], v[180:183], v[94:97]
	v_mfma_f32_16x16x32_bf16 v[90:93], v[212:215], v[180:183], v[90:93]
	v_mfma_f32_16x16x32_bf16 v[78:81], v[204:207], v[188:191], v[78:81]
	v_mfma_f32_16x16x32_bf16 v[74:77], v[212:215], v[188:191], v[74:77]
	v_mfma_f32_16x16x32_bf16 v[70:73], v[204:207], v[196:199], v[70:73]
	v_mfma_f32_16x16x32_bf16 v[66:69], v[212:215], v[196:199], v[66:69]
	s_mov_b32 m0, s13
	v_lshl_add_u64 v[216:217], v[220:221], 0, s[58:59]
	s_barrier
	ds_read_b128 v[162:165], v144 offset:49152
	ds_read_b128 v[168:171], v144 offset:50176
	ds_read_b128 v[176:179], v144 offset:51200
	ds_read_b128 v[180:183], v144 offset:52224
	ds_read_b128 v[184:187], v144 offset:53248
	ds_read_b128 v[188:191], v144 offset:54272
	ds_read_b128 v[192:195], v144 offset:55296
	ds_read_b128 v[196:199], v144 offset:56320
	global_load_lds_dwordx4 v[216:217], off
	v_lshl_add_u64 v[216:217], v[222:223], 0, s[58:59]
	s_mov_b32 m0, s16
	s_nop 0
	global_load_lds_dwordx4 v[216:217], off
	s_barrier
	s_waitcnt lgkmcnt(0)
	s_waitcnt lgkmcnt(0)
	v_mfma_f32_16x16x32_bf16 v[62:65], v[146:149], v[162:165], v[62:65]
	v_mfma_f32_16x16x32_bf16 v[58:61], v[154:157], v[162:165], v[58:61]
	v_mfma_f32_16x16x32_bf16 v[54:57], v[146:149], v[176:179], v[54:57]
	v_mfma_f32_16x16x32_bf16 v[50:53], v[154:157], v[176:179], v[50:53]
	v_mfma_f32_16x16x32_bf16 v[38:41], v[146:149], v[184:187], v[38:41]
	v_mfma_f32_16x16x32_bf16 v[34:37], v[154:157], v[184:187], v[34:37]
	v_mfma_f32_16x16x32_bf16 v[22:25], v[146:149], v[192:195], v[22:25]
	v_mfma_f32_16x16x32_bf16 v[18:21], v[154:157], v[192:195], v[18:21]
	v_mfma_f32_16x16x32_bf16 v[62:65], v[150:153], v[168:171], v[62:65]
	v_mfma_f32_16x16x32_bf16 v[58:61], v[158:161], v[168:171], v[58:61]
	v_mfma_f32_16x16x32_bf16 v[54:57], v[150:153], v[180:183], v[54:57]
	v_mfma_f32_16x16x32_bf16 v[50:53], v[158:161], v[180:183], v[50:53]
	v_mfma_f32_16x16x32_bf16 v[38:41], v[150:153], v[188:191], v[38:41]
	v_mfma_f32_16x16x32_bf16 v[34:37], v[158:161], v[188:191], v[34:37]
	v_mfma_f32_16x16x32_bf16 v[22:25], v[150:153], v[196:199], v[22:25]
	v_mfma_f32_16x16x32_bf16 v[18:21], v[158:161], v[196:199], v[18:21]
	s_barrier
	s_add_i32 s2, s3, s84
	v_lshl_add_u64 v[146:147], v[224:225], 0, s[58:59]
	s_mov_b32 m0, s2
	s_nop 0
	global_load_lds_dwordx4 v[146:147], off
	s_add_i32 m0, s2, 0x2000
	v_lshl_add_u64 v[146:147], v[226:227], 0, s[58:59]
	global_load_lds_dwordx4 v[146:147], off
	s_waitcnt vmcnt(6)
	s_barrier
	v_mfma_f32_16x16x32_bf16 v[46:49], v[200:203], v[162:165], v[46:49]
	v_mfma_f32_16x16x32_bf16 v[42:45], v[208:211], v[162:165], v[42:45]
	v_mfma_f32_16x16x32_bf16 v[30:33], v[200:203], v[176:179], v[30:33]
	v_mfma_f32_16x16x32_bf16 v[26:29], v[208:211], v[176:179], v[26:29]
	v_mfma_f32_16x16x32_bf16 v[14:17], v[200:203], v[184:187], v[14:17]
	v_mfma_f32_16x16x32_bf16 v[10:13], v[208:211], v[184:187], v[10:13]
	v_mfma_f32_16x16x32_bf16 v[6:9], v[200:203], v[192:195], v[6:9]
	v_mfma_f32_16x16x32_bf16 v[2:5], v[208:211], v[192:195], v[2:5]
	v_mfma_f32_16x16x32_bf16 v[46:49], v[204:207], v[168:171], v[46:49]
	v_mfma_f32_16x16x32_bf16 v[42:45], v[212:215], v[168:171], v[42:45]
	v_mfma_f32_16x16x32_bf16 v[30:33], v[204:207], v[180:183], v[30:33]
	v_mfma_f32_16x16x32_bf16 v[26:29], v[212:215], v[180:183], v[26:29]
	v_mfma_f32_16x16x32_bf16 v[14:17], v[204:207], v[188:191], v[14:17]
	v_mfma_f32_16x16x32_bf16 v[10:13], v[212:215], v[188:191], v[10:13]
	v_mfma_f32_16x16x32_bf16 v[6:9], v[204:207], v[196:199], v[6:9]
	v_mfma_f32_16x16x32_bf16 v[2:5], v[212:215], v[196:199], v[2:5]
	s_add_u32 s28, s28, 0x100
	s_addc_u32 s29, s29, 0
	s_add_u32 s37, s37, 0x100
	s_addc_u32 s18, s18, 0
	s_cmp_ge_u32 s95, s38
	s_mov_b32 s19, s95
	s_barrier
	s_cbranch_scc0 .LBB0_544
